# conv tile: counted waits so top-halo SiLU math overlaps the in-flight main x-row loads
# baseline (speedup 1.0000x reference)
; #define LAS __attribute__((address_space(3)))
; __device__ __forceinline__ void conv_tile(const Params& p, int l, int item, const bf16* PROJ, bf16* CV, LAS float* sl) {
;     ...
;     const int m0 = item * 32, b = m0 / SEQ, s0 = m0 % SEQ;
;     LAS float* part = sl; LAS float* stat = sl + 512;
;     float u[62];
; #pragma unroll
;     for (int rr = 0; rr < 62; ++rr) { const int sq = s0 - 15 + rr; const bool ok = sq >= 0 && sq < SEQ; const bf16* pr = PROJ + (size_t)(b * SEQ + (ok ? sq : s0)) * NIN;
;         const float a = bf2f(pr[PB_A + c]), g = bf2f(pr[PB_G + c]); u[rr] = ok ? a / (1.0f + __expf(-g)) : 0.f; }
.LBB0_299:
	v_readlane_b32 s1, v252, 60
	v_readlane_b32 s12, v254, 62
	s_or_b32 s0, s0, s1
	v_readlane_b32 s13, v254, 63
	s_mov_b32 s9, s13
	s_lshl_b32 s8, s0, 5
	v_readlane_b32 s14, v255, 0
	v_readlane_b32 s15, v255, 1
	v_readlane_b32 s16, v255, 2
	v_readlane_b32 s17, v255, 3
	v_readlane_b32 s18, v255, 4
	v_readlane_b32 s19, v255, 5
	v_readlane_b32 s20, v255, 6
	v_readlane_b32 s21, v255, 7
	v_readlane_b32 s22, v255, 8
	v_readlane_b32 s23, v255, 9
	v_readlane_b32 s24, v255, 10
	v_readlane_b32 s25, v255, 11
	v_readlane_b32 s26, v255, 12
	v_readlane_b32 s27, v255, 13
	s_mov_b64 s[12:13], s[8:9]
	v_writelane_b32 v254, s12, 62
	v_mov_b32_e32 v2, v188
	s_and_b32 s1, s8, 0xfe0
	v_writelane_b32 v255, s14, 0
	v_writelane_b32 v255, s15, 1
	v_writelane_b32 v255, s16, 2
	v_writelane_b32 v255, s17, 3
	v_writelane_b32 v255, s18, 4
	v_writelane_b32 v255, s19, 5
	v_writelane_b32 v255, s20, 6
	v_writelane_b32 v255, s21, 7
	v_writelane_b32 v255, s22, 8
	v_writelane_b32 v255, s23, 9
	v_writelane_b32 v255, s24, 10
	v_writelane_b32 v255, s25, 11
	v_writelane_b32 v254, s13, 63
	v_writelane_b32 v255, s26, 12
	v_writelane_b32 v255, s27, 13
	v_readlane_b32 s12, v254, 6
	s_and_b32 s0, s8, 0x7ffff000
	s_add_i32 s8, s1, -15
	v_ashrrev_i32_e32 v3, 31, v2
	v_readlane_b32 s13, v254, 7
	v_mov_b32_e32 v26, 0
	s_cmpk_gt_u32 s8, 0xfff
	v_lshl_add_u64 v[4:5], v[2:3], 1, s[12:13]
	v_mov_b32_e32 v28, 0
	v_add_co_u32_e32 v164, vcc, 0xe00, v4
	s_nop 1
	v_addc_co_u32_e32 v165, vcc, 0, v5, vcc
	s_add_i32 s8, s1, -15
	s_cmpk_gt_u32 s8, 0xfff
	s_cselect_b32 s8, s1, s8
	s_or_b32 s8, s8, s0
	v_mad_u64_u32 v[6:7], s[8:9], s8, v195, v[164:165]
	global_load_ushort v208, v[6:7], off offset:512
	global_load_ushort v209, v[6:7], off offset:-512
	s_add_i32 s8, s1, -14
	s_cmpk_gt_u32 s8, 0xfff
	s_cselect_b32 s8, s1, s8
	s_or_b32 s8, s8, s0
	v_mad_u64_u32 v[6:7], s[8:9], s8, v195, v[164:165]
	global_load_ushort v210, v[6:7], off offset:512
	global_load_ushort v211, v[6:7], off offset:-512
	s_add_i32 s8, s1, -13
	s_cmpk_gt_u32 s8, 0xfff
	s_cselect_b32 s8, s1, s8
	s_or_b32 s8, s8, s0
	v_mad_u64_u32 v[6:7], s[8:9], s8, v195, v[164:165]
	global_load_ushort v212, v[6:7], off offset:512
	global_load_ushort v213, v[6:7], off offset:-512
	s_add_i32 s8, s1, -12
	s_cmpk_gt_u32 s8, 0xfff
	s_cselect_b32 s8, s1, s8
	s_or_b32 s8, s8, s0
	v_mad_u64_u32 v[6:7], s[8:9], s8, v195, v[164:165]
	global_load_ushort v214, v[6:7], off offset:512
	global_load_ushort v215, v[6:7], off offset:-512
	s_add_i32 s8, s1, -11
	s_cmpk_gt_u32 s8, 0xfff
	s_cselect_b32 s8, s1, s8
	s_or_b32 s8, s8, s0
	v_mad_u64_u32 v[6:7], s[8:9], s8, v195, v[164:165]
	global_load_ushort v216, v[6:7], off offset:512
	global_load_ushort v217, v[6:7], off offset:-512
	s_add_i32 s8, s1, -10
	s_cmpk_gt_u32 s8, 0xfff
	s_cselect_b32 s8, s1, s8
	s_or_b32 s8, s8, s0
	v_mad_u64_u32 v[6:7], s[8:9], s8, v195, v[164:165]
	global_load_ushort v218, v[6:7], off offset:512
	global_load_ushort v219, v[6:7], off offset:-512
	s_add_i32 s8, s1, -9
	s_cmpk_gt_u32 s8, 0xfff
	s_cselect_b32 s8, s1, s8
	s_or_b32 s8, s8, s0
	v_mad_u64_u32 v[6:7], s[8:9], s8, v195, v[164:165]
	global_load_ushort v220, v[6:7], off offset:512
	global_load_ushort v221, v[6:7], off offset:-512
	s_add_i32 s8, s1, -8
	s_cmpk_gt_u32 s8, 0xfff
	s_cselect_b32 s8, s1, s8
	s_or_b32 s8, s8, s0
	v_mad_u64_u32 v[6:7], s[8:9], s8, v195, v[164:165]
	global_load_ushort v222, v[6:7], off offset:512
	global_load_ushort v223, v[6:7], off offset:-512
	s_add_i32 s8, s1, -7
	s_cmpk_gt_u32 s8, 0xfff
	s_cselect_b32 s8, s1, s8
	s_or_b32 s8, s8, s0
	v_mad_u64_u32 v[6:7], s[8:9], s8, v195, v[164:165]
	global_load_ushort v224, v[6:7], off offset:512
	global_load_ushort v225, v[6:7], off offset:-512
	s_add_i32 s8, s1, -6
	s_cmpk_gt_u32 s8, 0xfff
	s_cselect_b32 s8, s1, s8
	s_or_b32 s8, s8, s0
	v_mad_u64_u32 v[6:7], s[8:9], s8, v195, v[164:165]
	global_load_ushort v226, v[6:7], off offset:512
	global_load_ushort v227, v[6:7], off offset:-512
	s_add_i32 s8, s1, -5
	s_cmpk_gt_u32 s8, 0xfff
	s_cselect_b32 s8, s1, s8
	s_or_b32 s8, s8, s0
	v_mad_u64_u32 v[6:7], s[8:9], s8, v195, v[164:165]
	global_load_ushort v228, v[6:7], off offset:512
	global_load_ushort v229, v[6:7], off offset:-512
	s_add_i32 s8, s1, -4
	s_cmpk_gt_u32 s8, 0xfff
	s_cselect_b32 s8, s1, s8
	s_or_b32 s8, s8, s0
	v_mad_u64_u32 v[6:7], s[8:9], s8, v195, v[164:165]
	global_load_ushort v230, v[6:7], off offset:512
	global_load_ushort v231, v[6:7], off offset:-512
	s_add_i32 s8, s1, -3
	s_cmpk_gt_u32 s8, 0xfff
	s_cselect_b32 s8, s1, s8
	s_or_b32 s8, s8, s0
	v_mad_u64_u32 v[6:7], s[8:9], s8, v195, v[164:165]
	global_load_ushort v232, v[6:7], off offset:512
	global_load_ushort v233, v[6:7], off offset:-512
	s_add_i32 s8, s1, -2
	s_cmpk_gt_u32 s8, 0xfff
	s_cselect_b32 s8, s1, s8
	s_or_b32 s8, s8, s0
	v_mad_u64_u32 v[6:7], s[8:9], s8, v195, v[164:165]
	global_load_ushort v234, v[6:7], off offset:512
	global_load_ushort v235, v[6:7], off offset:-512
	s_add_i32 s8, s1, -1
	s_cmpk_gt_u32 s8, 0xfff
	s_cselect_b32 s8, s1, s8
	s_or_b32 s8, s8, s0
	v_mad_u64_u32 v[6:7], s[8:9], s8, v195, v[164:165]
	global_load_ushort v236, v[6:7], off offset:512
	global_load_ushort v237, v[6:7], off offset:-512
	s_add_i32 s8, s1, 32
	s_cmpk_gt_u32 s8, 0xfff
	s_cselect_b32 s8, s1, s8
	s_or_b32 s8, s8, s0
	v_mad_u64_u32 v[6:7], s[8:9], s8, v195, v[164:165]
	global_load_ushort v238, v[6:7], off offset:512
	global_load_ushort v239, v[6:7], off offset:-512
	s_add_i32 s8, s1, 33
	s_cmpk_gt_u32 s8, 0xfff
	s_cselect_b32 s8, s1, s8
	s_or_b32 s8, s8, s0
	v_mad_u64_u32 v[6:7], s[8:9], s8, v195, v[164:165]
	global_load_ushort v240, v[6:7], off offset:512
	global_load_ushort v241, v[6:7], off offset:-512
; __device__ __forceinline__ void conv_tile(const Params& p, int l, int item, const bf16* PROJ, bf16* CV, LAS float* sl) {
;     ...
;     for (int rr = 0; rr < 62; ++rr) { const int sq = s0 - 15 + rr; const bool ok = sq >= 0 && sq < SEQ; const bf16* pr = PROJ + (size_t)(b * SEQ + (ok ? sq : s0)) * NIN;
;         const float a = bf2f(pr[PB_A + c]), g = bf2f(pr[PB_G + c]); u[rr] = ok ? a / (1.0f + __expf(-g)) : 0.f; }
	s_add_i32 s8, s1, 34
	s_cmpk_gt_u32 s8, 0xfff
	s_cselect_b32 s8, s1, s8
	s_or_b32 s8, s8, s0
	v_mad_u64_u32 v[6:7], s[8:9], s8, v195, v[164:165]
	global_load_ushort v242, v[6:7], off offset:512
	global_load_ushort v243, v[6:7], off offset:-512
	s_add_i32 s8, s1, 35
	s_cmpk_gt_u32 s8, 0xfff
	s_cselect_b32 s8, s1, s8
	s_or_b32 s8, s8, s0
	v_mad_u64_u32 v[6:7], s[8:9], s8, v195, v[164:165]
	global_load_ushort v244, v[6:7], off offset:512
	global_load_ushort v245, v[6:7], off offset:-512
	s_add_i32 s8, s1, 36
	s_cmpk_gt_u32 s8, 0xfff
	s_cselect_b32 s8, s1, s8
	s_or_b32 s8, s8, s0
	v_mad_u64_u32 v[6:7], s[8:9], s8, v195, v[164:165]
	global_load_ushort v246, v[6:7], off offset:512
	global_load_ushort v247, v[6:7], off offset:-512
	s_add_i32 s8, s1, 37
	s_cmpk_gt_u32 s8, 0xfff
	s_cselect_b32 s8, s1, s8
	s_or_b32 s8, s8, s0
	v_mad_u64_u32 v[6:7], s[8:9], s8, v195, v[164:165]
	global_load_ushort v248, v[6:7], off offset:512
	global_load_ushort v249, v[6:7], off offset:-512
	s_add_i32 s8, s1, 38
	s_cmpk_gt_u32 s8, 0xfff
	s_cselect_b32 s8, s1, s8
	s_or_b32 s8, s8, s0
	v_mad_u64_u32 v[6:7], s[8:9], s8, v195, v[164:165]
	global_load_ushort v141, v[6:7], off offset:512
	global_load_ushort v142, v[6:7], off offset:-512
	s_add_i32 s8, s1, 39
	s_cmpk_gt_u32 s8, 0xfff
	s_cselect_b32 s8, s1, s8
	s_or_b32 s8, s8, s0
	v_mad_u64_u32 v[6:7], s[8:9], s8, v195, v[164:165]
	global_load_ushort v143, v[6:7], off offset:512
	global_load_ushort v144, v[6:7], off offset:-512
	s_add_i32 s8, s1, 40
	s_cmpk_gt_u32 s8, 0xfff
	s_cselect_b32 s8, s1, s8
	s_or_b32 s8, s8, s0
	v_mad_u64_u32 v[6:7], s[8:9], s8, v195, v[164:165]
	global_load_ushort v145, v[6:7], off offset:512
	global_load_ushort v146, v[6:7], off offset:-512
	s_add_i32 s8, s1, 41
	s_cmpk_gt_u32 s8, 0xfff
	s_cselect_b32 s8, s1, s8
	s_or_b32 s8, s8, s0
	v_mad_u64_u32 v[6:7], s[8:9], s8, v195, v[164:165]
	global_load_ushort v147, v[6:7], off offset:512
	global_load_ushort v148, v[6:7], off offset:-512
	s_add_i32 s8, s1, 42
	s_cmpk_gt_u32 s8, 0xfff
	s_cselect_b32 s8, s1, s8
	s_or_b32 s8, s8, s0
	v_mad_u64_u32 v[6:7], s[8:9], s8, v195, v[164:165]
	global_load_ushort v149, v[6:7], off offset:512
	global_load_ushort v150, v[6:7], off offset:-512
	s_add_i32 s8, s1, 43
	s_cmpk_gt_u32 s8, 0xfff
	s_cselect_b32 s8, s1, s8
	s_or_b32 s8, s8, s0
	v_mad_u64_u32 v[6:7], s[8:9], s8, v195, v[164:165]
	global_load_ushort v151, v[6:7], off offset:512
	global_load_ushort v152, v[6:7], off offset:-512
	s_add_i32 s8, s1, 44
	s_cmpk_gt_u32 s8, 0xfff
	s_cselect_b32 s8, s1, s8
	s_or_b32 s8, s8, s0
	v_mad_u64_u32 v[6:7], s[8:9], s8, v195, v[164:165]
	global_load_ushort v153, v[6:7], off offset:512
	global_load_ushort v156, v[6:7], off offset:-512
	s_add_i32 s8, s1, 45
	s_cmpk_gt_u32 s8, 0xfff
	s_cselect_b32 s8, s1, s8
	s_or_b32 s8, s8, s0
	v_mad_u64_u32 v[6:7], s[8:9], s8, v195, v[164:165]
	global_load_ushort v157, v[6:7], off offset:512
	global_load_ushort v158, v[6:7], off offset:-512
	s_add_i32 s8, s1, 46
	s_cmpk_gt_u32 s8, 0xfff
	s_cselect_b32 s8, s1, s8
	s_or_b32 s8, s8, s0
	v_mad_u64_u32 v[6:7], s[8:9], s8, v195, v[164:165]
	global_load_ushort v159, v[6:7], off offset:512
	global_load_ushort v160, v[6:7], off offset:-512
	v_readlane_b32 s80, v254, 62
	s_or_b32 s76, s80, 1
	s_or_b32 s74, s80, 2
	v_mad_u64_u32 v[8:9], s[8:9], s80, v195, v[4:5]
	v_add_co_u32_e32 v30, vcc, 0x1000, v8
	s_or_b32 s72, s80, 3
	s_nop 0
	v_addc_co_u32_e32 v31, vcc, 0, v9, vcc
	global_load_ushort v102, v[30:31], off
	global_load_ushort v101, v[8:9], off offset:3072
	v_mad_u64_u32 v[8:9], s[8:9], s76, v195, v[4:5]
	v_add_co_u32_e32 v30, vcc, 0x1000, v8
	s_or_b32 s70, s80, 4
	s_nop 0
	v_addc_co_u32_e32 v31, vcc, 0, v9, vcc
	global_load_ushort v100, v[30:31], off
	global_load_ushort v99, v[8:9], off offset:3072
	s_or_b32 s68, s80, 5
	v_mad_u64_u32 v[8:9], s[8:9], s72, v195, v[4:5]
	v_add_co_u32_e32 v32, vcc, 0x1000, v8
	s_or_b32 s66, s80, 6
	s_nop 0
	v_addc_co_u32_e32 v33, vcc, 0, v9, vcc
	global_load_ushort v98, v[32:33], off
	global_load_ushort v96, v[8:9], off offset:3072
	v_mad_u64_u32 v[8:9], s[8:9], s70, v195, v[4:5]
	v_add_co_u32_e32 v32, vcc, 0x1000, v8
	s_or_b32 s64, s80, 7
	s_nop 0
	v_addc_co_u32_e32 v33, vcc, 0, v9, vcc
	global_load_ushort v95, v[32:33], off
	global_load_ushort v94, v[8:9], off offset:3072
	v_mad_u64_u32 v[8:9], s[8:9], s68, v195, v[4:5]
	v_add_co_u32_e32 v32, vcc, 0x1000, v8
	s_or_b32 s62, s80, 8
	s_nop 0
	v_addc_co_u32_e32 v33, vcc, 0, v9, vcc
	global_load_ushort v93, v[32:33], off
	global_load_ushort v91, v[8:9], off offset:3072
	v_mad_u64_u32 v[8:9], s[8:9], s66, v195, v[4:5]
	v_add_co_u32_e32 v32, vcc, 0x1000, v8
	s_or_b32 s60, s80, 9
	s_nop 0
	v_addc_co_u32_e32 v33, vcc, 0, v9, vcc
	global_load_ushort v90, v[32:33], off
	global_load_ushort v81, v[8:9], off offset:3072
	v_mad_u64_u32 v[8:9], s[8:9], s64, v195, v[4:5]
	v_add_co_u32_e32 v32, vcc, 0x1000, v8
	s_or_b32 s58, s80, 10
	s_nop 0
	v_addc_co_u32_e32 v33, vcc, 0, v9, vcc
	global_load_ushort v92, v[32:33], off
	global_load_ushort v89, v[8:9], off offset:3072
	v_mad_u64_u32 v[8:9], s[8:9], s62, v195, v[4:5]
	v_add_co_u32_e32 v32, vcc, 0x1000, v8
	s_or_b32 s56, s80, 11
	s_nop 0
	v_addc_co_u32_e32 v33, vcc, 0, v9, vcc
	global_load_ushort v88, v[32:33], off
	global_load_ushort v77, v[8:9], off offset:3072
	v_mad_u64_u32 v[8:9], s[8:9], s60, v195, v[4:5]
	v_add_co_u32_e32 v32, vcc, 0x1000, v8
	s_or_b32 s54, s80, 12
	s_nop 0
	v_addc_co_u32_e32 v33, vcc, 0, v9, vcc
; __device__ __forceinline__ void conv_tile(const Params& p, int l, int item, const bf16* PROJ, bf16* CV, LAS float* sl) {
;     ...
;     for (int rr = 0; rr < 62; ++rr) { const int sq = s0 - 15 + rr; const bool ok = sq >= 0 && sq < SEQ; const bf16* pr = PROJ + (size_t)(b * SEQ + (ok ? sq : s0)) * NIN;
;         const float a = bf2f(pr[PB_A + c]), g = bf2f(pr[PB_G + c]); u[rr] = ok ? a / (1.0f + __expf(-g)) : 0.f; }
	global_load_ushort v87, v[32:33], off
	global_load_ushort v76, v[8:9], off offset:3072
	v_mad_u64_u32 v[8:9], s[8:9], s58, v195, v[4:5]
	v_add_co_u32_e32 v32, vcc, 0x1000, v8
	s_or_b32 s52, s80, 13
	s_nop 0
	v_addc_co_u32_e32 v33, vcc, 0, v9, vcc
	global_load_ushort v74, v[32:33], off
	global_load_ushort v71, v[8:9], off offset:3072
	v_mad_u64_u32 v[8:9], s[8:9], s56, v195, v[4:5]
	v_add_co_u32_e32 v32, vcc, 0x1000, v8
	s_or_b32 s50, s80, 14
	s_nop 0
	v_addc_co_u32_e32 v33, vcc, 0, v9, vcc
	global_load_ushort v86, v[32:33], off
	global_load_ushort v85, v[8:9], off offset:3072
	v_mad_u64_u32 v[8:9], s[8:9], s54, v195, v[4:5]
	v_add_co_u32_e32 v32, vcc, 0x1000, v8
	s_or_b32 s48, s80, 15
	s_nop 0
	v_addc_co_u32_e32 v33, vcc, 0, v9, vcc
	global_load_ushort v84, v[32:33], off
	global_load_ushort v69, v[8:9], off offset:3072
	v_mad_u64_u32 v[8:9], s[8:9], s52, v195, v[4:5]
	v_add_co_u32_e32 v32, vcc, 0x1000, v8
	s_or_b32 s46, s80, 16
	s_nop 0
	v_addc_co_u32_e32 v33, vcc, 0, v9, vcc
	global_load_ushort v83, v[32:33], off
	global_load_ushort v66, v[8:9], off offset:3072
	v_mad_u64_u32 v[8:9], s[8:9], s50, v195, v[4:5]
	v_add_co_u32_e32 v32, vcc, 0x1000, v8
	s_or_b32 s42, s80, 17
	s_nop 0
	v_addc_co_u32_e32 v33, vcc, 0, v9, vcc
	global_load_ushort v63, v[32:33], off
	global_load_ushort v61, v[8:9], off offset:3072
	v_mad_u64_u32 v[8:9], s[8:9], s48, v195, v[4:5]
	v_add_co_u32_e32 v32, vcc, 0x1000, v8
	s_or_b32 s40, s80, 18
	s_nop 0
	v_addc_co_u32_e32 v33, vcc, 0, v9, vcc
	global_load_ushort v82, v[32:33], off
	global_load_ushort v80, v[8:9], off offset:3072
	v_mad_u64_u32 v[8:9], s[8:9], s46, v195, v[4:5]
	v_add_co_u32_e32 v32, vcc, 0x1000, v8
	s_or_b32 s36, s80, 19
	s_nop 0
	v_addc_co_u32_e32 v33, vcc, 0, v9, vcc
	global_load_ushort v79, v[32:33], off
	global_load_ushort v58, v[8:9], off offset:3072
	v_mad_u64_u32 v[8:9], s[8:9], s42, v195, v[4:5]
	v_add_co_u32_e32 v32, vcc, 0x1000, v8
	s_or_b32 s34, s80, 20
	s_nop 0
	v_addc_co_u32_e32 v33, vcc, 0, v9, vcc
	global_load_ushort v78, v[32:33], off
	global_load_ushort v56, v[8:9], off offset:3072
	v_mad_u64_u32 v[8:9], s[8:9], s40, v195, v[4:5]
	v_add_co_u32_e32 v32, vcc, 0x1000, v8
	s_or_b32 s30, s80, 21
	s_nop 0
	v_addc_co_u32_e32 v33, vcc, 0, v9, vcc
	global_load_ushort v73, v[32:33], off
	global_load_ushort v57, v[8:9], off offset:3072
	v_mad_u64_u32 v[8:9], s[8:9], s36, v195, v[4:5]
	v_add_co_u32_e32 v32, vcc, 0x1000, v8
	s_or_b32 s28, s80, 22
	s_nop 0
	v_addc_co_u32_e32 v33, vcc, 0, v9, vcc
	global_load_ushort v75, v[32:33], off
	global_load_ushort v59, v[8:9], off offset:3072
	v_mad_u64_u32 v[8:9], s[8:9], s34, v195, v[4:5]
	v_add_co_u32_e32 v32, vcc, 0x1000, v8
	s_or_b32 s26, s80, 23
	s_nop 0
	v_addc_co_u32_e32 v33, vcc, 0, v9, vcc
	global_load_ushort v72, v[32:33], off
	global_load_ushort v60, v[8:9], off offset:3072
	v_mad_u64_u32 v[8:9], s[8:9], s30, v195, v[4:5]
	v_add_co_u32_e32 v32, vcc, 0x1000, v8
	s_or_b32 s24, s80, 24
	s_nop 0
	v_addc_co_u32_e32 v33, vcc, 0, v9, vcc
	global_load_ushort v70, v[32:33], off
	global_load_ushort v62, v[8:9], off offset:3072
	v_mad_u64_u32 v[8:9], s[8:9], s28, v195, v[4:5]
	v_add_co_u32_e32 v32, vcc, 0x1000, v8
	s_or_b32 s22, s80, 25
	s_nop 0
	v_addc_co_u32_e32 v33, vcc, 0, v9, vcc
	global_load_ushort v67, v[32:33], off
	global_load_ushort v64, v[8:9], off offset:3072
	v_mad_u64_u32 v[8:9], s[8:9], s26, v195, v[4:5]
	v_add_co_u32_e32 v32, vcc, 0x1000, v8
	s_or_b32 s20, s80, 26
	s_nop 0
	v_addc_co_u32_e32 v33, vcc, 0, v9, vcc
	global_load_ushort v68, v[32:33], off
	global_load_ushort v65, v[8:9], off offset:3072
	v_mad_u64_u32 v[8:9], s[8:9], s24, v195, v[4:5]
	v_add_co_u32_e32 v32, vcc, 0x1000, v8
	s_or_b32 s18, s80, 27
	s_nop 0
	v_addc_co_u32_e32 v33, vcc, 0, v9, vcc
	global_load_ushort v55, v[32:33], off
	global_load_ushort v54, v[8:9], off offset:3072
	v_mad_u64_u32 v[8:9], s[8:9], s22, v195, v[4:5]
	v_add_co_u32_e32 v32, vcc, 0x1000, v8
	s_or_b32 s16, s80, 28
	s_nop 0
	v_addc_co_u32_e32 v33, vcc, 0, v9, vcc
	global_load_ushort v53, v[32:33], off
	global_load_ushort v52, v[8:9], off offset:3072
	v_mad_u64_u32 v[8:9], s[8:9], s20, v195, v[4:5]
	v_add_co_u32_e32 v32, vcc, 0x1000, v8
	s_or_b32 s14, s80, 29
	s_nop 0
	v_addc_co_u32_e32 v33, vcc, 0, v9, vcc
	global_load_ushort v44, v[32:33], off
	global_load_ushort v38, v[8:9], off offset:3072
	v_mad_u64_u32 v[8:9], s[8:9], s18, v195, v[4:5]
	v_add_co_u32_e32 v32, vcc, 0x1000, v8
	s_or_b32 s12, s80, 30
	s_nop 0
	v_addc_co_u32_e32 v33, vcc, 0, v9, vcc
	global_load_ushort v47, v[32:33], off
	global_load_ushort v41, v[8:9], off offset:3072
	v_mad_u64_u32 v[8:9], s[8:9], s16, v195, v[4:5]
	v_add_co_u32_e32 v32, vcc, 0x1000, v8
	v_readlane_b32 s81, v254, 63
	s_nop 0
	v_addc_co_u32_e32 v33, vcc, 0, v9, vcc
	global_load_ushort v37, v[32:33], off
	global_load_ushort v36, v[8:9], off offset:3072
	v_readlane_b32 s82, v255, 0
	s_waitcnt vmcnt(63)
	s_add_i32 s8, s1, -15
	s_cmpk_gt_u32 s8, 0xfff
	s_cbranch_scc1 .LBB0_301
	v_lshlrev_b32_e32 v7, 16, v208
	v_mul_f32_e32 v7, 0xbfb8aa3b, v7
	v_exp_f32_e32 v7, v7
	v_lshlrev_b32_e32 v6, 16, v209
	v_add_f32_e32 v7, 1.0, v7
	v_div_scale_f32 v8, s[8:9], v7, v7, v6
	v_rcp_f32_e32 v9, v8
	v_div_scale_f32 v13, vcc, v6, v7, v6
	v_fma_f32 v14, -v8, v9, 1.0
	v_fmac_f32_e32 v9, v14, v9
	v_mul_f32_e32 v14, v13, v9
	v_fma_f32 v15, -v8, v14, v13
	v_fmac_f32_e32 v14, v15, v9
	v_fma_f32 v8, -v8, v14, v13
	v_div_fmas_f32 v8, v8, v9, v14
	v_div_fixup_f32 v28, v8, v7, v6

; __device__ __forceinline__ void conv_tile(const Params& p, int l, int item, const bf16* PROJ, bf16* CV, LAS float* sl) {
;     ...
;     for (int rr = 0; rr < 62; ++rr) { const int sq = s0 - 15 + rr; const bool ok = sq >= 0 && sq < SEQ; const bf16* pr = PROJ + (size_t)(b * SEQ + (ok ? sq : s0)) * NIN;
;         const float a = bf2f(pr[PB_A + c]), g = bf2f(pr[PB_G + c]); u[rr] = ok ? a / (1.0f + __expf(-g)) : 0.f; }
.LBB0_329:
	v_mad_u64_u32 v[8:9], s[8:9], s74, v195, v[4:5]
	v_add_co_u32_e32 v30, vcc, 0x1000, v8
	s_nop 0
	s_nop 0
	v_addc_co_u32_e32 v31, vcc, 0, v9, vcc
	global_load_ushort v97, v[30:31], off
	s_nop 0
	global_load_ushort v30, v[8:9], off offset:3072
	v_mad_u64_u32 v[8:9], s[8:9], s14, v195, v[4:5]
	v_add_co_u32_e32 v32, vcc, 0x1000, v8
	s_nop 0
	s_nop 0
	v_addc_co_u32_e32 v33, vcc, 0, v9, vcc
	global_load_ushort v34, v[32:33], off
	global_load_ushort v13, v[8:9], off offset:3072
	v_mad_u64_u32 v[8:9], s[8:9], s12, v195, v[4:5]
	v_add_co_u32_e32 v32, vcc, 0x1000, v8
	s_or_b32 s8, s80, 31
	s_nop 0
	v_addc_co_u32_e32 v33, vcc, 0, v9, vcc
	global_load_ushort v31, v[32:33], off
	global_load_ushort v29, v[8:9], off offset:3072
	v_mad_u64_u32 v[8:9], s[78:79], s8, v195, v[4:5]
	v_add_co_u32_e32 v32, vcc, 0x1000, v8
	s_cmpk_eq_i32 s1, 0xfe0
	s_nop 0
	v_addc_co_u32_e32 v33, vcc, 0, v9, vcc
	global_load_ushort v33, v[32:33], off
	s_nop 0
	global_load_ushort v32, v[8:9], off offset:3072
	s_waitcnt vmcnt(63)
	v_readlane_b32 s83, v255, 1
	v_readlane_b32 s84, v255, 2
	v_readlane_b32 s85, v255, 3
	v_readlane_b32 s86, v255, 4
	v_readlane_b32 s87, v255, 5
	v_readlane_b32 s88, v255, 6
	v_readlane_b32 s89, v255, 7
	v_readlane_b32 s90, v255, 8
	v_readlane_b32 s91, v255, 9
	v_readlane_b32 s92, v255, 10
	v_readlane_b32 s93, v255, 11
	v_readlane_b32 s94, v255, 12
	v_readlane_b32 s95, v255, 13
	s_cbranch_scc1 .LBB0_352
	v_lshlrev_b32_e32 v7, 16, v238
	v_mul_f32_e32 v7, 0xbfb8aa3b, v7
	v_exp_f32_e32 v7, v7
	v_lshlrev_b32_e32 v6, 16, v239
	v_add_f32_e32 v7, 1.0, v7
	v_div_scale_f32 v8, s[78:79], v7, v7, v6
	v_rcp_f32_e32 v9, v8
	v_div_scale_f32 v35, vcc, v6, v7, v6
	v_fma_f32 v39, -v8, v9, 1.0
	v_fmac_f32_e32 v9, v39, v9
	v_mul_f32_e32 v39, v35, v9
	v_fma_f32 v40, -v8, v39, v35
	v_fmac_f32_e32 v39, v40, v9
	v_fma_f32 v8, -v8, v39, v35
	v_div_fmas_f32 v8, v8, v9, v39
	v_div_fixup_f32 v6, v8, v7, v6
	v_mov_b32_e32 v7, 0
	s_cmpk_gt_u32 s1, 0xfde
	v_mov_b32_e32 v8, 0
	s_cbranch_scc0 .LBB0_353

; __device__ __forceinline__ void conv_tile(const Params& p, int l, int item, const bf16* PROJ, bf16* CV, LAS float* sl) {
;     ...
;     for (int rr = 0; rr < 62; ++rr) { const int sq = s0 - 15 + rr; const bool ok = sq >= 0 && sq < SEQ; const bf16* pr = PROJ + (size_t)(b * SEQ + (ok ? sq : s0)) * NIN;
;         const float a = bf2f(pr[PB_A + c]), g = bf2f(pr[PB_G + c]); u[rr] = ok ? a / (1.0f + __expf(-g)) : 0.f; }
.LBB0_345:
	s_waitcnt vmcnt(62)
	v_lshlrev_b32_e32 v4, 16, v102
	v_mul_f32_e32 v4, 0xbfb8aa3b, v4
	v_exp_f32_e32 v4, v4
	v_lshlrev_b32_e32 v5, 16, v101
	s_waitcnt vmcnt(61)
	v_lshlrev_b32_e32 v100, 16, v100
	v_mul_f32_e32 v100, 0xbfb8aa3b, v100
	v_add_f32_e32 v4, 1.0, v4
	v_div_scale_f32 v101, s[0:1], v4, v4, v5
	v_rcp_f32_e32 v102, v101
	v_exp_f32_e32 v100, v100
	v_div_scale_f32 v103, vcc, v5, v4, v5
	v_fma_f32 v104, -v101, v102, 1.0
	v_fmac_f32_e32 v102, v104, v102
	v_mul_f32_e32 v104, v103, v102
	v_fma_f32 v105, -v101, v104, v103
	v_fmac_f32_e32 v104, v105, v102
	s_waitcnt vmcnt(60)
	v_lshlrev_b32_e32 v99, 16, v99
	v_add_f32_e32 v100, 1.0, v100
	v_fma_f32 v101, -v101, v104, v103
	v_div_scale_f32 v103, s[0:1], v100, v100, v99
	v_rcp_f32_e32 v105, v103
	s_waitcnt vmcnt(7)
	v_lshlrev_b32_e32 v97, 16, v97
	v_mul_f32_e32 v97, 0xbfb8aa3b, v97
	v_div_fmas_f32 v101, v101, v102, v104
	v_exp_f32_e32 v97, v97
	v_div_fixup_f32 v121, v101, v4, v5
	v_fma_f32 v4, -v103, v105, 1.0
	v_fmac_f32_e32 v105, v4, v105
	v_div_scale_f32 v4, vcc, v99, v100, v99
	v_mul_f32_e32 v5, v4, v105
	v_fma_f32 v101, -v103, v5, v4
	s_waitcnt vmcnt(6)
	v_lshlrev_b32_e32 v30, 16, v30
	v_add_f32_e32 v97, 1.0, v97
	v_fmac_f32_e32 v5, v101, v105
	v_div_scale_f32 v101, s[0:1], v97, v97, v30
	v_rcp_f32_e32 v102, v101
	s_waitcnt vmcnt(6)
	v_lshlrev_b32_e32 v98, 16, v98
	v_fma_f32 v4, -v103, v5, v4
	v_mul_f32_e32 v98, 0xbfb8aa3b, v98
	v_div_fmas_f32 v4, v4, v105, v5
	v_exp_f32_e32 v98, v98
	v_div_fixup_f32 v119, v4, v100, v99
	v_fma_f32 v4, -v101, v102, 1.0
	v_fmac_f32_e32 v102, v4, v102
	v_div_scale_f32 v4, vcc, v30, v97, v30
	v_mul_f32_e32 v5, v4, v102
	v_fma_f32 v99, -v101, v5, v4
	s_waitcnt vmcnt(6)
	v_lshlrev_b32_e32 v96, 16, v96
	v_add_f32_e32 v98, 1.0, v98
	v_fmac_f32_e32 v5, v99, v102
	v_div_scale_f32 v99, s[0:1], v98, v98, v96
	v_rcp_f32_e32 v100, v99
	s_waitcnt vmcnt(6)
	v_lshlrev_b32_e32 v95, 16, v95
	v_fma_f32 v4, -v101, v5, v4
	v_mul_f32_e32 v95, 0xbfb8aa3b, v95
	v_div_fmas_f32 v4, v4, v102, v5
	v_exp_f32_e32 v95, v95
	v_div_fixup_f32 v30, v4, v97, v30
	v_fma_f32 v4, -v99, v100, 1.0
	v_fmac_f32_e32 v100, v4, v100
	v_div_scale_f32 v4, vcc, v96, v98, v96
	v_mul_f32_e32 v5, v4, v100
	v_fma_f32 v97, -v99, v5, v4
	s_waitcnt vmcnt(6)
	v_lshlrev_b32_e32 v94, 16, v94
	v_add_f32_e32 v95, 1.0, v95
	v_fmac_f32_e32 v5, v97, v100
	v_div_scale_f32 v97, s[0:1], v95, v95, v94
	v_fma_f32 v4, -v99, v5, v4
	v_rcp_f32_e32 v99, v97
	s_waitcnt vmcnt(6)
	v_lshlrev_b32_e32 v93, 16, v93
	v_div_fmas_f32 v4, v4, v100, v5
	v_mul_f32_e32 v93, 0xbfb8aa3b, v93
	v_div_fixup_f32 v111, v4, v98, v96
	v_fma_f32 v4, -v97, v99, 1.0
	v_exp_f32_e32 v93, v93
	v_fmac_f32_e32 v99, v4, v99
	v_div_scale_f32 v4, vcc, v94, v95, v94
	v_mul_f32_e32 v5, v4, v99
	v_fma_f32 v96, -v97, v5, v4
	v_fmac_f32_e32 v5, v96, v99
	s_waitcnt vmcnt(6)
	v_lshlrev_b32_e32 v96, 16, v91
	v_add_f32_e32 v93, 1.0, v93
	v_fma_f32 v4, -v97, v5, v4
	v_div_scale_f32 v97, s[0:1], v93, v93, v96
	v_rcp_f32_e32 v98, v97
	s_waitcnt vmcnt(6)
	v_lshlrev_b32_e32 v90, 16, v90
	v_div_fmas_f32 v4, v4, v99, v5
	v_mul_f32_e32 v90, 0xbfb8aa3b, v90
	v_div_fixup_f32 v91, v4, v95, v94
	v_fma_f32 v4, -v97, v98, 1.0
	v_exp_f32_e32 v90, v90
	v_fmac_f32_e32 v98, v4, v98
	v_div_scale_f32 v4, vcc, v96, v93, v96
	v_mul_f32_e32 v5, v4, v98
	v_fma_f32 v94, -v97, v5, v4
	v_fmac_f32_e32 v5, v94, v98
	s_waitcnt vmcnt(6)
	v_lshlrev_b32_e32 v81, 16, v81
	v_add_f32_e32 v94, 1.0, v90
	v_div_scale_f32 v95, s[0:1], v94, v94, v81
	v_fma_f32 v4, -v97, v5, v4
	v_rcp_f32_e32 v97, v95
	s_waitcnt vmcnt(6)
	v_lshlrev_b32_e32 v92, 16, v92
	v_mul_f32_e32 v92, 0xbfb8aa3b, v92
	v_div_fmas_f32 v4, v4, v98, v5
	v_exp_f32_e32 v92, v92
	v_div_fixup_f32 v90, v4, v93, v96
	v_fma_f32 v4, -v95, v97, 1.0
	v_fmac_f32_e32 v97, v4, v97
	v_div_scale_f32 v4, vcc, v81, v94, v81
	v_mul_f32_e32 v5, v4, v97
	v_fma_f32 v93, -v95, v5, v4
	s_waitcnt vmcnt(6)
	v_lshlrev_b32_e32 v89, 16, v89
	v_add_f32_e32 v92, 1.0, v92
	v_fmac_f32_e32 v5, v93, v97
	v_div_scale_f32 v93, s[0:1], v92, v92, v89
	v_fma_f32 v4, -v95, v5, v4
	v_rcp_f32_e32 v95, v93
	v_div_fmas_f32 v4, v4, v97, v5
	s_waitcnt vmcnt(6)
	v_lshlrev_b32_e32 v88, 16, v88
	v_div_fixup_f32 v81, v4, v94, v81
	v_fma_f32 v4, -v93, v95, 1.0
	v_mul_f32_e32 v88, 0xbfb8aa3b, v88
	v_fmac_f32_e32 v95, v4, v95
	v_div_scale_f32 v4, vcc, v89, v92, v89
	v_exp_f32_e32 v88, v88
	v_mul_f32_e32 v5, v4, v95
	v_fma_f32 v94, -v93, v5, v4
	v_fmac_f32_e32 v5, v94, v95
	v_fma_f32 v4, -v93, v5, v4
	s_waitcnt vmcnt(6)
	v_lshlrev_b32_e32 v93, 16, v77
	v_add_f32_e32 v88, 1.0, v88
	v_div_scale_f32 v94, s[0:1], v88, v88, v93
	v_rcp_f32_e32 v96, v94
	s_waitcnt vmcnt(6)
	v_lshlrev_b32_e32 v87, 16, v87
	v_div_fmas_f32 v4, v4, v95, v5
	v_mul_f32_e32 v87, 0xbfb8aa3b, v87
	v_div_fixup_f32 v77, v4, v92, v89
	v_fma_f32 v4, -v94, v96, 1.0
	v_exp_f32_e32 v87, v87
	v_fmac_f32_e32 v96, v4, v96
	v_div_scale_f32 v4, vcc, v93, v88, v93
	v_mul_f32_e32 v5, v4, v96
	v_fma_f32 v89, -v94, v5, v4
	v_fmac_f32_e32 v5, v89, v96
	s_waitcnt vmcnt(6)
	v_lshlrev_b32_e32 v89, 16, v76
	v_add_f32_e32 v87, 1.0, v87
	v_div_scale_f32 v92, s[0:1], v87, v87, v89
	v_fma_f32 v4, -v94, v5, v4
	v_rcp_f32_e32 v94, v92
	s_waitcnt vmcnt(6)
	v_lshlrev_b32_e32 v74, 16, v74
	v_div_fmas_f32 v4, v4, v96, v5
	v_mul_f32_e32 v74, 0xbfb8aa3b, v74
	v_div_fixup_f32 v76, v4, v88, v93
	v_fma_f32 v4, -v92, v94, 1.0
	v_exp_f32_e32 v74, v74
	v_fmac_f32_e32 v94, v4, v94
	v_div_scale_f32 v4, vcc, v89, v87, v89
	v_mul_f32_e32 v5, v4, v94
	v_fma_f32 v88, -v92, v5, v4
	v_fmac_f32_e32 v5, v88, v94
	s_waitcnt vmcnt(6)
	v_lshlrev_b32_e32 v71, 16, v71
	v_add_f32_e32 v88, 1.0, v74
	v_fma_f32 v4, -v92, v5, v4
	v_div_scale_f32 v92, s[0:1], v88, v88, v71
	v_rcp_f32_e32 v93, v92
	s_waitcnt vmcnt(6)
; __device__ __forceinline__ void conv_tile(const Params& p, int l, int item, const bf16* PROJ, bf16* CV, LAS float* sl) {
;     ...
;     for (int rr = 0; rr < 62; ++rr) { const int sq = s0 - 15 + rr; const bool ok = sq >= 0 && sq < SEQ; const bf16* pr = PROJ + (size_t)(b * SEQ + (ok ? sq : s0)) * NIN;
;         const float a = bf2f(pr[PB_A + c]), g = bf2f(pr[PB_G + c]); u[rr] = ok ? a / (1.0f + __expf(-g)) : 0.f; }
	v_lshlrev_b32_e32 v86, 16, v86
	v_mul_f32_e32 v86, 0xbfb8aa3b, v86
	v_div_fmas_f32 v4, v4, v94, v5
	v_exp_f32_e32 v86, v86
	v_div_fixup_f32 v74, v4, v87, v89
	v_fma_f32 v4, -v92, v93, 1.0
	v_fmac_f32_e32 v93, v4, v93
	v_div_scale_f32 v4, vcc, v71, v88, v71
	v_mul_f32_e32 v5, v4, v93
	v_fma_f32 v87, -v92, v5, v4
	s_waitcnt vmcnt(6)
	v_lshlrev_b32_e32 v85, 16, v85
	v_add_f32_e32 v86, 1.0, v86
	v_fmac_f32_e32 v5, v87, v93
	v_div_scale_f32 v87, s[0:1], v86, v86, v85
	v_rcp_f32_e32 v89, v87
	v_fma_f32 v4, -v92, v5, v4
	v_div_fmas_f32 v4, v4, v93, v5
	s_waitcnt vmcnt(6)
	v_lshlrev_b32_e32 v84, 16, v84
	v_div_fixup_f32 v71, v4, v88, v71
	v_fma_f32 v4, -v87, v89, 1.0
	v_mul_f32_e32 v84, 0xbfb8aa3b, v84
	v_fmac_f32_e32 v89, v4, v89
	v_div_scale_f32 v4, vcc, v85, v86, v85
	v_exp_f32_e32 v84, v84
	v_mul_f32_e32 v5, v4, v89
	v_fma_f32 v88, -v87, v5, v4
	v_fmac_f32_e32 v5, v88, v89
	v_fma_f32 v4, -v87, v5, v4
	s_waitcnt vmcnt(6)
	v_lshlrev_b32_e32 v87, 16, v69
	v_add_f32_e32 v84, 1.0, v84
	v_div_scale_f32 v88, s[0:1], v84, v84, v87
	v_rcp_f32_e32 v92, v88
	s_waitcnt vmcnt(6)
	v_lshlrev_b32_e32 v83, 16, v83
	v_div_fmas_f32 v4, v4, v89, v5
	v_mul_f32_e32 v83, 0xbfb8aa3b, v83
	v_div_fixup_f32 v69, v4, v86, v85
	v_fma_f32 v4, -v88, v92, 1.0
	v_exp_f32_e32 v83, v83
	v_fmac_f32_e32 v92, v4, v92
	v_div_scale_f32 v4, vcc, v87, v84, v87
	v_mul_f32_e32 v5, v4, v92
	v_fma_f32 v85, -v88, v5, v4
	v_fmac_f32_e32 v5, v85, v92
	s_waitcnt vmcnt(6)
	v_lshlrev_b32_e32 v85, 16, v66
	v_add_f32_e32 v83, 1.0, v83
	v_div_scale_f32 v86, s[0:1], v83, v83, v85
	v_fma_f32 v4, -v88, v5, v4
	v_rcp_f32_e32 v88, v86
	s_waitcnt vmcnt(6)
	v_lshlrev_b32_e32 v63, 16, v63
	v_div_fmas_f32 v4, v4, v92, v5
	v_mul_f32_e32 v63, 0xbfb8aa3b, v63
	v_div_fixup_f32 v66, v4, v84, v87
	v_fma_f32 v4, -v86, v88, 1.0
	v_exp_f32_e32 v63, v63
	v_fmac_f32_e32 v88, v4, v88
	v_div_scale_f32 v4, vcc, v85, v83, v85
	v_mul_f32_e32 v5, v4, v88
	v_fma_f32 v84, -v86, v5, v4
	v_fmac_f32_e32 v5, v84, v88
	s_waitcnt vmcnt(6)
	v_lshlrev_b32_e32 v61, 16, v61
	v_add_f32_e32 v84, 1.0, v63
	v_fma_f32 v4, -v86, v5, v4
	v_div_scale_f32 v86, s[0:1], v84, v84, v61
	v_rcp_f32_e32 v87, v86
	s_waitcnt vmcnt(6)
	v_lshlrev_b32_e32 v82, 16, v82
	v_mul_f32_e32 v82, 0xbfb8aa3b, v82
	v_div_fmas_f32 v4, v4, v88, v5
	v_exp_f32_e32 v82, v82
	v_div_fixup_f32 v63, v4, v83, v85
	v_fma_f32 v4, -v86, v87, 1.0
	v_fmac_f32_e32 v87, v4, v87
	v_div_scale_f32 v4, vcc, v61, v84, v61
	v_mul_f32_e32 v5, v4, v87
	v_fma_f32 v83, -v86, v5, v4
	s_waitcnt vmcnt(6)
	v_lshlrev_b32_e32 v80, 16, v80
	v_add_f32_e32 v82, 1.0, v82
	v_fmac_f32_e32 v5, v83, v87
	v_div_scale_f32 v83, s[0:1], v82, v82, v80
	v_rcp_f32_e32 v85, v83
	v_fma_f32 v4, -v86, v5, v4
	v_div_fmas_f32 v4, v4, v87, v5
	s_waitcnt vmcnt(6)
	v_lshlrev_b32_e32 v79, 16, v79
	v_div_fixup_f32 v61, v4, v84, v61
	v_fma_f32 v4, -v83, v85, 1.0
	v_mul_f32_e32 v79, 0xbfb8aa3b, v79
	v_fmac_f32_e32 v85, v4, v85
	v_div_scale_f32 v4, vcc, v80, v82, v80
	v_exp_f32_e32 v79, v79
	v_mul_f32_e32 v5, v4, v85
	v_fma_f32 v84, -v83, v5, v4
	v_fmac_f32_e32 v5, v84, v85
	v_fma_f32 v4, -v83, v5, v4
	s_waitcnt vmcnt(6)
	v_lshlrev_b32_e32 v83, 16, v58
	v_add_f32_e32 v79, 1.0, v79
	v_div_scale_f32 v84, s[0:1], v79, v79, v83
	v_rcp_f32_e32 v86, v84
	s_waitcnt vmcnt(6)
	v_lshlrev_b32_e32 v78, 16, v78
	v_div_fmas_f32 v4, v4, v85, v5
	v_mul_f32_e32 v78, 0xbfb8aa3b, v78
	v_div_fixup_f32 v58, v4, v82, v80
	v_fma_f32 v4, -v84, v86, 1.0
	v_exp_f32_e32 v78, v78
	v_fmac_f32_e32 v86, v4, v86
	v_div_scale_f32 v4, vcc, v83, v79, v83
	v_mul_f32_e32 v5, v4, v86
	v_fma_f32 v80, -v84, v5, v4
	v_fmac_f32_e32 v5, v80, v86
	s_waitcnt vmcnt(6)
	v_lshlrev_b32_e32 v80, 16, v56
	v_add_f32_e32 v78, 1.0, v78
	v_div_scale_f32 v82, s[0:1], v78, v78, v80
	v_fma_f32 v4, -v84, v5, v4
	v_rcp_f32_e32 v84, v82
	s_waitcnt vmcnt(6)
	v_lshlrev_b32_e32 v73, 16, v73
	v_div_fmas_f32 v4, v4, v86, v5
	v_mul_f32_e32 v73, 0xbfb8aa3b, v73
	v_div_fixup_f32 v56, v4, v79, v83
	v_fma_f32 v4, -v82, v84, 1.0
	v_exp_f32_e32 v73, v73
	v_fmac_f32_e32 v84, v4, v84
	v_div_scale_f32 v4, vcc, v80, v78, v80
	v_mul_f32_e32 v5, v4, v84
	v_fma_f32 v79, -v82, v5, v4
	v_fmac_f32_e32 v5, v79, v84
	s_waitcnt vmcnt(6)
	v_lshlrev_b32_e32 v79, 16, v57
	v_add_f32_e32 v73, 1.0, v73
	v_fma_f32 v4, -v82, v5, v4
	v_div_scale_f32 v82, s[0:1], v73, v73, v79
	v_rcp_f32_e32 v83, v82
	s_waitcnt vmcnt(6)
	v_lshlrev_b32_e32 v75, 16, v75
	v_div_fmas_f32 v4, v4, v84, v5
	v_mul_f32_e32 v75, 0xbfb8aa3b, v75
	v_div_fixup_f32 v57, v4, v78, v80
	v_fma_f32 v4, -v82, v83, 1.0
	v_exp_f32_e32 v75, v75
	v_fmac_f32_e32 v83, v4, v83
	v_div_scale_f32 v4, vcc, v79, v73, v79
	v_mul_f32_e32 v5, v4, v83
	v_fma_f32 v78, -v82, v5, v4
	v_fmac_f32_e32 v5, v78, v83
	s_waitcnt vmcnt(6)
	v_lshlrev_b32_e32 v78, 16, v59
	v_add_f32_e32 v75, 1.0, v75
	v_div_scale_f32 v80, s[0:1], v75, v75, v78
	v_fma_f32 v4, -v82, v5, v4
	v_rcp_f32_e32 v82, v80
	s_waitcnt vmcnt(6)
	v_lshlrev_b32_e32 v72, 16, v72
	v_div_fmas_f32 v4, v4, v83, v5
	v_mul_f32_e32 v72, 0xbfb8aa3b, v72
	v_div_fixup_f32 v59, v4, v73, v79
	v_fma_f32 v4, -v80, v82, 1.0
	v_exp_f32_e32 v72, v72
	v_fmac_f32_e32 v82, v4, v82
	v_div_scale_f32 v4, vcc, v78, v75, v78
	v_mul_f32_e32 v5, v4, v82
	v_fma_f32 v73, -v80, v5, v4
	v_fmac_f32_e32 v5, v73, v82
	s_waitcnt vmcnt(6)
	v_lshlrev_b32_e32 v73, 16, v60
	v_add_f32_e32 v72, 1.0, v72
	v_div_scale_f32 v79, s[0:1], v72, v72, v73
	v_fma_f32 v4, -v80, v5, v4
	v_rcp_f32_e32 v80, v79
	s_waitcnt vmcnt(6)
	v_lshlrev_b32_e32 v70, 16, v70
	v_div_fmas_f32 v4, v4, v82, v5
	v_mul_f32_e32 v70, 0xbfb8aa3b, v70
	v_div_fixup_f32 v60, v4, v75, v78
	v_fma_f32 v4, -v79, v80, 1.0
	v_exp_f32_e32 v70, v70
	v_fmac_f32_e32 v80, v4, v80
	v_div_scale_f32 v4, vcc, v73, v72, v73
	v_mul_f32_e32 v5, v4, v80
	v_fma_f32 v75, -v79, v5, v4
	v_fmac_f32_e32 v5, v75, v80
	s_waitcnt vmcnt(6)
; __device__ __forceinline__ void conv_tile(const Params& p, int l, int item, const bf16* PROJ, bf16* CV, LAS float* sl) {
;     ...
;     for (int rr = 0; rr < 62; ++rr) { const int sq = s0 - 15 + rr; const bool ok = sq >= 0 && sq < SEQ; const bf16* pr = PROJ + (size_t)(b * SEQ + (ok ? sq : s0)) * NIN;
;         const float a = bf2f(pr[PB_A + c]), g = bf2f(pr[PB_G + c]); u[rr] = ok ? a / (1.0f + __expf(-g)) : 0.f; }
;     float w[31];
; #pragma unroll
;     for (int j = 0; j < 31; ++j) w[j] = p.conv_dw[(size_t)(l * 31 + j) * CC + c];
;     const float bias = p.conv_dw_b[l * CC + c];
	v_lshlrev_b32_e32 v75, 16, v62
	v_add_f32_e32 v70, 1.0, v70
	v_div_scale_f32 v78, s[0:1], v70, v70, v75
	v_fma_f32 v4, -v79, v5, v4
	v_rcp_f32_e32 v79, v78
	s_waitcnt vmcnt(6)
	v_lshlrev_b32_e32 v67, 16, v67
	v_div_fmas_f32 v4, v4, v80, v5
	v_mul_f32_e32 v67, 0xbfb8aa3b, v67
	v_div_fixup_f32 v62, v4, v72, v73
	v_fma_f32 v4, -v78, v79, 1.0
	v_exp_f32_e32 v67, v67
	v_fmac_f32_e32 v79, v4, v79
	v_div_scale_f32 v4, vcc, v75, v70, v75
	v_mul_f32_e32 v5, v4, v79
	v_fma_f32 v72, -v78, v5, v4
	v_fmac_f32_e32 v5, v72, v79
	s_waitcnt vmcnt(6)
	v_lshlrev_b32_e32 v72, 16, v64
	v_add_f32_e32 v67, 1.0, v67
	v_div_scale_f32 v73, s[0:1], v67, v67, v72
	v_fma_f32 v4, -v78, v5, v4
	v_rcp_f32_e32 v78, v73
	s_waitcnt vmcnt(6)
	v_lshlrev_b32_e32 v68, 16, v68
	v_div_fmas_f32 v4, v4, v79, v5
	v_mul_f32_e32 v68, 0xbfb8aa3b, v68
	v_div_fixup_f32 v64, v4, v70, v75
	v_fma_f32 v4, -v73, v78, 1.0
	v_exp_f32_e32 v68, v68
	v_fmac_f32_e32 v78, v4, v78
	v_div_scale_f32 v4, vcc, v72, v67, v72
	v_mul_f32_e32 v5, v4, v78
	v_fma_f32 v70, -v73, v5, v4
	v_fmac_f32_e32 v5, v70, v78
	s_waitcnt vmcnt(6)
	v_lshlrev_b32_e32 v70, 16, v65
	v_add_f32_e32 v68, 1.0, v68
	v_fma_f32 v4, -v73, v5, v4
	v_div_scale_f32 v73, s[0:1], v68, v68, v70
	v_rcp_f32_e32 v75, v73
	s_waitcnt vmcnt(6)
	v_lshlrev_b32_e32 v55, 16, v55
	v_mul_f32_e32 v55, 0xbfb8aa3b, v55
	v_div_fmas_f32 v4, v4, v78, v5
	v_exp_f32_e32 v55, v55
	v_div_fixup_f32 v65, v4, v67, v72
	v_fma_f32 v4, -v73, v75, 1.0
	v_fmac_f32_e32 v75, v4, v75
	v_div_scale_f32 v4, vcc, v70, v68, v70
	v_mul_f32_e32 v5, v4, v75
	v_fma_f32 v67, -v73, v5, v4
	s_waitcnt vmcnt(6)
	v_lshlrev_b32_e32 v54, 16, v54
	v_add_f32_e32 v55, 1.0, v55
	v_fmac_f32_e32 v5, v67, v75
	v_div_scale_f32 v72, s[0:1], v55, v55, v54
	v_fma_f32 v4, -v73, v5, v4
	v_rcp_f32_e32 v73, v72
	s_waitcnt vmcnt(6)
	v_lshlrev_b32_e32 v53, 16, v53
	v_mul_f32_e32 v53, 0xbfb8aa3b, v53
	v_div_fmas_f32 v4, v4, v75, v5
	v_exp_f32_e32 v53, v53
	v_div_fixup_f32 v67, v4, v68, v70
	v_fma_f32 v4, -v72, v73, 1.0
	v_fmac_f32_e32 v73, v4, v73
	v_div_scale_f32 v4, vcc, v54, v55, v54
	v_mul_f32_e32 v5, v4, v73
	v_fma_f32 v68, -v72, v5, v4
	s_waitcnt vmcnt(6)
	v_lshlrev_b32_e32 v52, 16, v52
	v_add_f32_e32 v53, 1.0, v53
	v_fmac_f32_e32 v5, v68, v73
	v_div_scale_f32 v70, s[0:1], v53, v53, v52
	v_fma_f32 v4, -v72, v5, v4
	v_rcp_f32_e32 v72, v70
	s_waitcnt vmcnt(6)
	v_lshlrev_b32_e32 v44, 16, v44
	v_mul_f32_e32 v44, 0xbfb8aa3b, v44
	v_div_fmas_f32 v4, v4, v73, v5
	v_exp_f32_e32 v44, v44
	v_div_fixup_f32 v68, v4, v55, v54
	v_fma_f32 v4, -v70, v72, 1.0
	v_fmac_f32_e32 v72, v4, v72
	v_div_scale_f32 v4, vcc, v52, v53, v52
	v_mul_f32_e32 v5, v4, v72
	v_fma_f32 v54, -v70, v5, v4
	s_waitcnt vmcnt(6)
	v_lshlrev_b32_e32 v38, 16, v38
	v_add_f32_e32 v44, 1.0, v44
	v_fmac_f32_e32 v5, v54, v72
	v_div_scale_f32 v54, s[0:1], v44, v44, v38
	v_rcp_f32_e32 v55, v54
	s_waitcnt vmcnt(6)
	v_lshlrev_b32_e32 v47, 16, v47
	v_fma_f32 v4, -v70, v5, v4
	v_mul_f32_e32 v47, 0xbfb8aa3b, v47
	v_div_fmas_f32 v4, v4, v72, v5
	v_exp_f32_e32 v47, v47
	v_div_fixup_f32 v70, v4, v53, v52
	v_fma_f32 v4, -v54, v55, 1.0
	v_fmac_f32_e32 v55, v4, v55
	v_div_scale_f32 v4, vcc, v38, v44, v38
	v_mul_f32_e32 v5, v4, v55
	v_fma_f32 v52, -v54, v5, v4
	s_waitcnt vmcnt(6)
	v_lshlrev_b32_e32 v41, 16, v41
	v_add_f32_e32 v47, 1.0, v47
	v_fmac_f32_e32 v5, v52, v55
	v_div_scale_f32 v52, s[0:1], v47, v47, v41
	v_rcp_f32_e32 v53, v52
	s_waitcnt vmcnt(6)
	v_lshlrev_b32_e32 v37, 16, v37
	v_fma_f32 v4, -v54, v5, v4
	v_mul_f32_e32 v37, 0xbfb8aa3b, v37
	v_div_fmas_f32 v4, v4, v55, v5
	v_exp_f32_e32 v37, v37
	v_div_fixup_f32 v72, v4, v44, v38
	v_fma_f32 v4, -v52, v53, 1.0
	v_fmac_f32_e32 v53, v4, v53
	v_div_scale_f32 v4, vcc, v41, v47, v41
	v_mul_f32_e32 v5, v4, v53
	v_fma_f32 v38, -v52, v5, v4
	s_waitcnt vmcnt(6)
	v_lshlrev_b32_e32 v36, 16, v36
	v_add_f32_e32 v37, 1.0, v37
	v_fmac_f32_e32 v5, v38, v53
	v_div_scale_f32 v38, s[0:1], v37, v37, v36
	v_rcp_f32_e32 v44, v38
	v_fma_f32 v4, -v52, v5, v4
	v_div_fmas_f32 v4, v4, v53, v5
	s_waitcnt vmcnt(5)
	v_lshlrev_b32_e32 v34, 16, v34
	v_div_fixup_f32 v73, v4, v47, v41
	v_fma_f32 v4, -v38, v44, 1.0
	v_mul_f32_e32 v34, 0xbfb8aa3b, v34
	v_fmac_f32_e32 v44, v4, v44
	v_div_scale_f32 v4, vcc, v36, v37, v36
	v_exp_f32_e32 v34, v34
	v_mul_f32_e32 v5, v4, v44
	v_fma_f32 v41, -v38, v5, v4
	v_fmac_f32_e32 v5, v41, v44
	v_fma_f32 v4, -v38, v5, v4
	s_waitcnt vmcnt(4)
	v_lshlrev_b32_e32 v38, 16, v13
	v_add_f32_e32 v34, 1.0, v34
	v_div_scale_f32 v41, s[0:1], v34, v34, v38
	v_div_fmas_f32 v4, v4, v44, v5
	v_div_fixup_f32 v75, v4, v37, v36
	v_lshl_add_u64 v[36:37], v[2:3], 2, s[2:3]
	s_movk_i32 s0, 0x1000
	v_add_co_u32_e32 v4, vcc, s0, v36
	s_movk_i32 s0, 0x2000
	s_nop 0
	v_addc_co_u32_e32 v5, vcc, 0, v37, vcc
	v_add_co_u32_e32 v52, vcc, s0, v36
	s_movk_i32 s0, 0x3000
	s_nop 0
	v_addc_co_u32_e32 v53, vcc, 0, v37, vcc
	v_add_co_u32_e32 v54, vcc, s0, v36
	s_movk_i32 s0, 0x4000
	s_nop 0
	v_addc_co_u32_e32 v55, vcc, 0, v37, vcc
	s_waitcnt vmcnt(0)
; __device__ __forceinline__ void conv_tile(const Params& p, int l, int item, const bf16* PROJ, bf16* CV, LAS float* sl) {
;     ...
;         const float a = bf2f(pr[PB_A + c]), g = bf2f(pr[PB_G + c]); u[rr] = ok ? a / (1.0f + __expf(-g)) : 0.f; }
;     float w[31];
; #pragma unroll
;     for (int j = 0; j < 31; ++j) w[j] = p.conv_dw[(size_t)(l * 31 + j) * CC + c];
;     const float bias = p.conv_dw_b[l * CC + c];
;     float y[32], y2[32];
; #pragma unroll
;     for (int t = 0; t < 32; ++t) { float acc = bias;
; #pragma unroll
;         for (int j = 0; j < 31; ++j) acc = fmaf(u[t + j], w[j], acc);
;         y[t] = acc; y2[t] = acc * acc; }
	global_load_dword v80, v[36:37], off
	global_load_dword v79, v[36:37], off offset:2048
	global_load_dword v78, v[4:5], off offset:2048
	v_add_co_u32_e32 v4, vcc, s0, v36
	s_movk_i32 s0, 0x5000
	s_nop 0
	v_addc_co_u32_e32 v5, vcc, 0, v37, vcc
	v_add_co_u32_e32 v96, vcc, s0, v36
	s_movk_i32 s0, 0x6000
	s_nop 0
	v_addc_co_u32_e32 v97, vcc, 0, v37, vcc
	v_add_co_u32_e32 v92, vcc, s0, v36
	s_movk_i32 s0, 0x7000
	s_nop 0
	v_addc_co_u32_e32 v93, vcc, 0, v37, vcc
	global_load_dword v89, v[52:53], off offset:-4096
	global_load_dword v88, v[52:53], off
	global_load_dword v87, v[52:53], off offset:2048
	global_load_dword v86, v[4:5], off offset:-4096
	global_load_dword v84, v[4:5], off
	global_load_dword v83, v[4:5], off offset:2048
	global_load_dword v85, v[92:93], off offset:-4096
	global_load_dword v82, v[92:93], off
	v_add_co_u32_e32 v52, vcc, s0, v36
	s_mov_b32 s0, 0x8000
	s_nop 0
	v_addc_co_u32_e32 v53, vcc, 0, v37, vcc
	v_add_co_u32_e32 v94, vcc, s0, v36
	s_mov_b32 s0, 0x9000
	s_nop 0
	v_addc_co_u32_e32 v95, vcc, 0, v37, vcc
	v_add_co_u32_e32 v114, vcc, s0, v36
	s_mov_b32 s0, 0xa000
	s_nop 0
	v_addc_co_u32_e32 v115, vcc, 0, v37, vcc
	v_add_co_u32_e32 v108, vcc, s0, v36
	s_mov_b32 s0, 0xb000
	s_nop 0
	v_addc_co_u32_e32 v109, vcc, 0, v37, vcc
	v_add_co_u32_e32 v116, vcc, s0, v36
	s_mov_b32 s0, 0xc000
	s_nop 0
	v_addc_co_u32_e32 v117, vcc, 0, v37, vcc
	v_add_co_u32_e32 v122, vcc, s0, v36
	v_readlane_b32 s0, v255, 24
	v_readlane_b32 s80, v251, 33
	v_readlane_b32 s84, v251, 37
	v_add_u32_e32 v4, s0, v2
	v_ashrrev_i32_e32 v5, 31, v4
	v_readlane_b32 s85, v251, 38
	v_addc_co_u32_e32 v123, vcc, 0, v37, vcc
	s_nop 0
	v_lshl_add_u64 v[98:99], v[4:5], 2, s[84:85]
	global_load_dword v13, v[98:99], off
	global_load_dword v107, v[92:93], off offset:2048
	global_load_dword v105, v[94:95], off offset:-4096
	global_load_dword v102, v[94:95], off
	global_load_dword v101, v[94:95], off offset:2048
	s_nop 0
	global_load_dword v98, v[108:109], off offset:-4096
	global_load_dword v94, v[108:109], off
	global_load_dword v93, v[108:109], off offset:2048
	global_load_dword v92, v[122:123], off offset:-4096
	global_load_dword v112, v[54:55], off offset:2048
	global_load_dword v110, v[96:97], off offset:2048
	s_nop 0
	global_load_dword v109, v[52:53], off offset:2048
	global_load_dword v108, v[114:115], off offset:2048
	global_load_dword v96, v[116:117], off offset:2048
	s_mov_b32 s0, 0xd000
	v_add_co_u32_e32 v52, vcc, s0, v36
	s_mov_b32 s0, 0xe000
	s_nop 0
	v_addc_co_u32_e32 v53, vcc, 0, v37, vcc
	v_add_co_u32_e32 v54, vcc, s0, v36
	s_mov_b32 s0, 0xf000
	s_nop 0
	v_addc_co_u32_e32 v55, vcc, 0, v37, vcc
	global_load_dword v95, v[52:53], off offset:2048
	global_load_dword v106, v[122:123], off
	global_load_dword v104, v[122:123], off offset:2048
	global_load_dword v103, v[54:55], off offset:-4096
	global_load_dword v99, v[54:55], off
	global_load_dword v97, v[54:55], off offset:2048
	v_add_co_u32_e32 v36, vcc, s0, v36
	v_rcp_f32_e32 v47, v41
	s_nop 0
	v_addc_co_u32_e32 v37, vcc, 0, v37, vcc
	global_load_dword v100, v[36:37], off
	s_waitcnt vmcnt(35)
	v_lshlrev_b32_e32 v31, 16, v31
	v_mul_f32_e32 v31, 0xbfb8aa3b, v31
	v_fma_f32 v44, -v41, v47, 1.0
	v_exp_f32_e32 v31, v31
	v_fmac_f32_e32 v47, v44, v47
	v_div_scale_f32 v36, vcc, v38, v34, v38
	v_mul_f32_e32 v37, v36, v47
	v_fma_f32 v44, -v41, v37, v36
	v_readlane_b32 s1, v255, 25
	v_fmac_f32_e32 v37, v44, v47
	s_waitcnt vmcnt(34)
	v_lshlrev_b32_e32 v29, 16, v29
	v_add_f32_e32 v31, 1.0, v31
	v_fma_f32 v36, -v41, v37, v36
	v_div_scale_f32 v41, s[0:1], v31, v31, v29
	v_rcp_f32_e32 v44, v41
	s_waitcnt vmcnt(33)
	v_lshlrev_b32_e32 v33, 16, v33
	v_mul_f32_e32 v33, 0xbfb8aa3b, v33
	v_div_fmas_f32 v36, v36, v47, v37
	v_exp_f32_e32 v33, v33
	v_div_fixup_f32 v115, v36, v34, v38
	v_fma_f32 v34, -v41, v44, 1.0
	v_fmac_f32_e32 v44, v34, v44
	v_div_scale_f32 v34, vcc, v29, v31, v29
	v_mul_f32_e32 v36, v34, v44
	v_fma_f32 v37, -v41, v36, v34
	s_waitcnt vmcnt(32)
	v_lshlrev_b32_e32 v32, 16, v32
	v_add_f32_e32 v33, 1.0, v33
	v_fmac_f32_e32 v36, v37, v44
	v_div_scale_f32 v37, s[0:1], v33, v33, v32
	v_rcp_f32_e32 v38, v37
	v_fma_f32 v34, -v41, v36, v34
	v_div_fmas_f32 v34, v34, v44, v36
	v_div_fixup_f32 v116, v34, v31, v29
	v_fma_f32 v29, -v37, v38, 1.0
	v_fmac_f32_e32 v38, v29, v38
	v_div_scale_f32 v29, vcc, v32, v33, v32
	v_mul_f32_e32 v31, v29, v38
	v_fma_f32 v34, -v37, v31, v29
	v_fmac_f32_e32 v31, v34, v38
	v_fma_f32 v29, -v37, v31, v29
	v_div_fmas_f32 v29, v29, v38, v31
	v_div_fixup_f32 v117, v29, v33, v32
	v_and_b32_e32 v114, 32, v2
	s_waitcnt vmcnt(20)
	v_fma_f32 v55, v28, v80, v13
	v_fmac_f32_e32 v55, v26, v79
	v_fma_f32 v54, v26, v80, v13
	v_fmac_f32_e32 v55, v27, v89
	v_fmac_f32_e32 v54, v27, v79
	v_fma_f32 v53, v27, v80, v13
	v_fmac_f32_e32 v55, v24, v78
	v_fmac_f32_e32 v54, v24, v89
	v_fmac_f32_e32 v53, v24, v79
	v_fma_f32 v52, v24, v80, v13
	v_fmac_f32_e32 v55, v25, v88
	v_fmac_f32_e32 v54, v25, v78
	v_fmac_f32_e32 v53, v25, v89
	v_fmac_f32_e32 v52, v25, v79
	v_fma_f32 v44, v25, v80, v13
	v_fmac_f32_e32 v55, v22, v87
	v_fmac_f32_e32 v54, v22, v88
	v_fmac_f32_e32 v53, v22, v78
	v_fmac_f32_e32 v52, v22, v89
	v_fmac_f32_e32 v44, v22, v79
	v_fma_f32 v47, v22, v80, v13
	v_fmac_f32_e32 v55, v23, v86
	v_fmac_f32_e32 v54, v23, v87
	v_fmac_f32_e32 v53, v23, v88
	v_fmac_f32_e32 v52, v23, v78
	v_fmac_f32_e32 v44, v23, v89
	v_fmac_f32_e32 v47, v23, v79
	v_fma_f32 v36, v23, v80, v13
	s_waitcnt vmcnt(11)
; __device__ __forceinline__ void conv_tile(const Params& p, int l, int item, const bf16* PROJ, bf16* CV, LAS float* sl) {
;     ...
;     for (int t = 0; t < 32; ++t) { float acc = bias;
; #pragma unroll
;         for (int j = 0; j < 31; ++j) acc = fmaf(u[t + j], w[j], acc);
;         y[t] = acc; y2[t] = acc * acc; }
	v_fmac_f32_e32 v55, v20, v112
	v_fmac_f32_e32 v54, v20, v86
	v_fmac_f32_e32 v53, v20, v87
	v_fmac_f32_e32 v52, v20, v88
	v_fmac_f32_e32 v44, v20, v78
	v_fmac_f32_e32 v47, v20, v89
	v_fmac_f32_e32 v36, v20, v79
	v_fma_f32 v37, v20, v80, v13
	v_fmac_f32_e32 v55, v21, v84
	v_fmac_f32_e32 v54, v21, v112
	v_fmac_f32_e32 v53, v21, v86
	v_fmac_f32_e32 v52, v21, v87
	v_fmac_f32_e32 v44, v21, v88
	v_fmac_f32_e32 v47, v21, v78
	v_fmac_f32_e32 v36, v21, v89
	v_fmac_f32_e32 v37, v21, v79
	v_fma_f32 v38, v21, v80, v13
	v_fmac_f32_e32 v55, v18, v83
	v_fmac_f32_e32 v54, v18, v84
	v_fmac_f32_e32 v53, v18, v112
	v_fmac_f32_e32 v52, v18, v86
	v_fmac_f32_e32 v44, v18, v87
	v_fmac_f32_e32 v47, v18, v88
	v_fmac_f32_e32 v36, v18, v78
	v_fmac_f32_e32 v37, v18, v89
	v_fmac_f32_e32 v38, v18, v79
	v_fma_f32 v41, v18, v80, v13
	v_fmac_f32_e32 v55, v19, v85
	v_fmac_f32_e32 v54, v19, v83
	v_fmac_f32_e32 v53, v19, v84
	v_fmac_f32_e32 v52, v19, v112
	v_fmac_f32_e32 v44, v19, v86
	v_fmac_f32_e32 v47, v19, v87
	v_fmac_f32_e32 v36, v19, v88
	v_fmac_f32_e32 v37, v19, v78
	v_fmac_f32_e32 v38, v19, v89
	v_fmac_f32_e32 v41, v19, v79
	v_fma_f32 v34, v19, v80, v13
	s_waitcnt vmcnt(10)
	v_fmac_f32_e32 v55, v16, v110
	v_fmac_f32_e32 v54, v16, v85
	v_fmac_f32_e32 v53, v16, v83
	v_fmac_f32_e32 v52, v16, v84
	v_fmac_f32_e32 v44, v16, v112
	v_fmac_f32_e32 v47, v16, v86
	v_fmac_f32_e32 v36, v16, v87
	v_fmac_f32_e32 v37, v16, v88
	v_fmac_f32_e32 v38, v16, v78
	v_fmac_f32_e32 v41, v16, v89
	v_fmac_f32_e32 v34, v16, v79
	v_fma_f32 v32, v16, v80, v13
	v_fmac_f32_e32 v55, v17, v82
	v_fmac_f32_e32 v54, v17, v110
	v_fmac_f32_e32 v53, v17, v85
	v_fmac_f32_e32 v52, v17, v83
	v_fmac_f32_e32 v44, v17, v84
	v_fmac_f32_e32 v47, v17, v112
	v_fmac_f32_e32 v36, v17, v86
	v_fmac_f32_e32 v37, v17, v87
	v_fmac_f32_e32 v38, v17, v88
	v_fmac_f32_e32 v41, v17, v78
	v_fmac_f32_e32 v34, v17, v89
	v_fmac_f32_e32 v32, v17, v79
	v_fma_f32 v31, v17, v80, v13
	v_fmac_f32_e32 v55, v14, v107
	v_fmac_f32_e32 v54, v14, v82
	v_fmac_f32_e32 v53, v14, v110
	v_fmac_f32_e32 v52, v14, v85
	v_fmac_f32_e32 v44, v14, v83
	v_fmac_f32_e32 v47, v14, v84
	v_fmac_f32_e32 v36, v14, v112
	v_fmac_f32_e32 v37, v14, v86
	v_fmac_f32_e32 v38, v14, v87
	v_fmac_f32_e32 v41, v14, v88
	v_fmac_f32_e32 v34, v14, v78
	v_fmac_f32_e32 v32, v14, v89
	v_fmac_f32_e32 v31, v14, v79
	v_fma_f32 v33, v14, v80, v13
	v_fmac_f32_e32 v55, v15, v105
	v_fmac_f32_e32 v54, v15, v107
	v_fmac_f32_e32 v53, v15, v82
	v_fmac_f32_e32 v52, v15, v110
	v_fmac_f32_e32 v44, v15, v85
	v_fmac_f32_e32 v47, v15, v83
	v_fmac_f32_e32 v36, v15, v84
	v_fmac_f32_e32 v37, v15, v112
	v_fmac_f32_e32 v38, v15, v86
	v_fmac_f32_e32 v41, v15, v87
	v_fmac_f32_e32 v34, v15, v88
	v_fmac_f32_e32 v32, v15, v78
	v_fmac_f32_e32 v31, v15, v89
	v_fmac_f32_e32 v33, v15, v79
	v_fma_f32 v29, v15, v80, v13
	s_waitcnt vmcnt(9)
	v_fmac_f32_e32 v55, v121, v109
	v_fmac_f32_e32 v54, v121, v105
	v_fmac_f32_e32 v53, v121, v107
	v_fmac_f32_e32 v52, v121, v82
	v_fmac_f32_e32 v44, v121, v110
	v_fmac_f32_e32 v47, v121, v85
	v_fmac_f32_e32 v36, v121, v83
	v_fmac_f32_e32 v37, v121, v84
	v_fmac_f32_e32 v38, v121, v112
	v_fmac_f32_e32 v41, v121, v86
	v_fmac_f32_e32 v34, v121, v87
	v_fmac_f32_e32 v32, v121, v88
	v_fmac_f32_e32 v31, v121, v78
	v_fmac_f32_e32 v33, v121, v89
	v_fmac_f32_e32 v29, v121, v79
	v_fma_f32 v28, v121, v80, v13
	v_fmac_f32_e32 v55, v119, v102
	v_fmac_f32_e32 v54, v119, v109
	v_fmac_f32_e32 v53, v119, v105
	v_fmac_f32_e32 v52, v119, v107
	v_fmac_f32_e32 v44, v119, v82
	v_fmac_f32_e32 v47, v119, v110
	v_fmac_f32_e32 v36, v119, v85
	v_fmac_f32_e32 v37, v119, v83
	v_fmac_f32_e32 v38, v119, v84
	v_fmac_f32_e32 v41, v119, v112
	v_fmac_f32_e32 v34, v119, v86
	v_fmac_f32_e32 v32, v119, v87
	v_fmac_f32_e32 v31, v119, v88
	v_fmac_f32_e32 v33, v119, v78
	v_fmac_f32_e32 v29, v119, v89
	v_fmac_f32_e32 v28, v119, v79
	v_fma_f32 v27, v119, v80, v13
	v_fmac_f32_e32 v55, v30, v101
	v_fmac_f32_e32 v54, v30, v102
	v_fmac_f32_e32 v53, v30, v109
	v_fmac_f32_e32 v52, v30, v105
	v_fmac_f32_e32 v44, v30, v107
	v_fmac_f32_e32 v47, v30, v82
	v_fmac_f32_e32 v36, v30, v110
	v_fmac_f32_e32 v37, v30, v85
	v_fmac_f32_e32 v38, v30, v83
	v_fmac_f32_e32 v41, v30, v84
	v_fmac_f32_e32 v34, v30, v112
	v_fmac_f32_e32 v32, v30, v86
	v_fmac_f32_e32 v31, v30, v87
	v_fmac_f32_e32 v33, v30, v88
	v_fmac_f32_e32 v29, v30, v78
	v_fmac_f32_e32 v28, v30, v89
	v_fmac_f32_e32 v27, v30, v79
	v_fma_f32 v30, v30, v80, v13
	v_fmac_f32_e32 v30, v111, v79
	v_fma_f32 v25, v111, v80, v13
	v_fma_f32 v24, v91, v80, v13
	v_fmac_f32_e32 v30, v91, v89
	v_fmac_f32_e32 v25, v91, v79
	v_fmac_f32_e32 v24, v90, v79
	v_fma_f32 v23, v90, v80, v13
	v_fmac_f32_e32 v30, v90, v78
	v_fmac_f32_e32 v25, v90, v89
	v_fmac_f32_e32 v24, v81, v89
	v_fmac_f32_e32 v23, v81, v79
	v_fma_f32 v26, v81, v80, v13
	v_fma_f32 v22, v71, v80, v13
	v_fmac_f32_e32 v30, v81, v88
	v_fmac_f32_e32 v25, v81, v78
	v_fmac_f32_e32 v24, v77, v78
	v_fmac_f32_e32 v23, v77, v89
	v_fmac_f32_e32 v26, v77, v79
	v_fma_f32 v21, v77, v80, v13
	v_fmac_f32_e32 v22, v69, v79
	v_fma_f32 v17, v69, v80, v13
	v_fma_f32 v18, v61, v80, v13
	v_fmac_f32_e32 v30, v77, v87
	v_fmac_f32_e32 v25, v77, v88
	v_fmac_f32_e32 v24, v76, v88
	v_fmac_f32_e32 v23, v76, v78
	v_fmac_f32_e32 v26, v76, v89
	v_fmac_f32_e32 v21, v76, v79
	v_fma_f32 v20, v76, v80, v13
	v_fma_f32 v19, v74, v80, v13
	v_fmac_f32_e32 v22, v66, v89
	v_fmac_f32_e32 v17, v66, v79
	v_fma_f32 v16, v66, v80, v13
	v_fma_f32 v15, v63, v80, v13
	v_fmac_f32_e32 v18, v58, v79
	v_fma_f32 v14, v58, v80, v13
	v_fmac_f32_e32 v13, v56, v80
	v_fmac_f32_e32 v30, v76, v86
	v_fmac_f32_e32 v25, v76, v87
	v_fmac_f32_e32 v24, v74, v87
	v_fmac_f32_e32 v23, v74, v88
; __device__ __forceinline__ void conv_tile(const Params& p, int l, int item, const bf16* PROJ, bf16* CV, LAS float* sl) {
;     ...
;     for (int t = 0; t < 32; ++t) { float acc = bias;
; #pragma unroll
;         for (int j = 0; j < 31; ++j) acc = fmaf(u[t + j], w[j], acc);
;         y[t] = acc; y2[t] = acc * acc; }
	v_fmac_f32_e32 v26, v74, v78
	v_fmac_f32_e32 v21, v74, v89
	v_fmac_f32_e32 v20, v74, v79
	v_fmac_f32_e32 v22, v63, v78
	v_fmac_f32_e32 v17, v63, v89
	v_fmac_f32_e32 v16, v63, v79
	v_fmac_f32_e32 v18, v56, v89
	v_fmac_f32_e32 v14, v56, v79
	v_fmac_f32_e32 v13, v57, v79
	v_fmac_f32_e32 v30, v74, v112
	v_fmac_f32_e32 v25, v74, v86
	v_fmac_f32_e32 v24, v71, v86
	v_fmac_f32_e32 v23, v71, v87
	v_fmac_f32_e32 v26, v71, v88
	v_fmac_f32_e32 v21, v71, v78
	v_fmac_f32_e32 v20, v71, v89
	v_fmac_f32_e32 v19, v71, v79
	v_fmac_f32_e32 v22, v61, v88
	v_fmac_f32_e32 v17, v61, v78
	v_fmac_f32_e32 v16, v61, v89
	v_fmac_f32_e32 v15, v61, v79
	v_fmac_f32_e32 v18, v57, v78
	v_fmac_f32_e32 v14, v57, v89
	v_fmac_f32_e32 v13, v59, v89
	v_fmac_f32_e32 v30, v71, v84
	v_fmac_f32_e32 v25, v71, v112
	v_fmac_f32_e32 v24, v69, v112
	v_fmac_f32_e32 v23, v69, v86
	v_fmac_f32_e32 v26, v69, v87
	v_fmac_f32_e32 v21, v69, v88
	v_fmac_f32_e32 v20, v69, v78
	v_fmac_f32_e32 v19, v69, v89
	v_fmac_f32_e32 v22, v58, v87
	v_fmac_f32_e32 v17, v58, v88
	v_fmac_f32_e32 v16, v58, v78
	v_fmac_f32_e32 v15, v58, v89
	v_fmac_f32_e32 v18, v59, v88
	v_fmac_f32_e32 v14, v59, v78
	v_fmac_f32_e32 v13, v60, v78
	v_fmac_f32_e32 v30, v69, v83
	v_fmac_f32_e32 v25, v69, v84
	v_fmac_f32_e32 v24, v66, v84
	v_fmac_f32_e32 v23, v66, v112
	v_fmac_f32_e32 v26, v66, v86
	v_fmac_f32_e32 v21, v66, v87
	v_fmac_f32_e32 v20, v66, v88
	v_fmac_f32_e32 v19, v66, v78
	v_fmac_f32_e32 v22, v56, v86
	v_fmac_f32_e32 v17, v56, v87
	v_fmac_f32_e32 v16, v56, v88
	v_fmac_f32_e32 v15, v56, v78
	v_fmac_f32_e32 v18, v60, v87
	v_fmac_f32_e32 v14, v60, v88
	v_fmac_f32_e32 v13, v62, v88
	v_fmac_f32_e32 v30, v66, v85
	v_fmac_f32_e32 v25, v66, v83
	v_fmac_f32_e32 v24, v63, v83
	v_fmac_f32_e32 v23, v63, v84
	v_fmac_f32_e32 v26, v63, v112
	v_fmac_f32_e32 v21, v63, v86
	v_fmac_f32_e32 v20, v63, v87
	v_fmac_f32_e32 v19, v63, v88
	v_fmac_f32_e32 v22, v57, v112
	v_fmac_f32_e32 v17, v57, v86
	v_fmac_f32_e32 v16, v57, v87
	v_fmac_f32_e32 v15, v57, v88
	v_fmac_f32_e32 v18, v62, v86
	v_fmac_f32_e32 v14, v62, v87
	v_fmac_f32_e32 v13, v64, v87
	v_fmac_f32_e32 v30, v63, v110
	v_fmac_f32_e32 v25, v63, v85
	v_fmac_f32_e32 v24, v61, v85
	v_fmac_f32_e32 v23, v61, v83
	v_fmac_f32_e32 v26, v61, v84
	v_fmac_f32_e32 v21, v61, v112
	v_fmac_f32_e32 v20, v61, v86
	v_fmac_f32_e32 v19, v61, v87
	v_fmac_f32_e32 v22, v59, v84
	v_fmac_f32_e32 v17, v59, v112
	v_fmac_f32_e32 v16, v59, v86
	v_fmac_f32_e32 v15, v59, v87
	v_fmac_f32_e32 v18, v64, v112
	v_fmac_f32_e32 v14, v64, v86
	v_fmac_f32_e32 v13, v65, v86
	v_fmac_f32_e32 v30, v61, v82
	v_fmac_f32_e32 v25, v61, v110
	v_fmac_f32_e32 v24, v58, v110
	v_fmac_f32_e32 v23, v58, v85
	v_fmac_f32_e32 v26, v58, v83
	v_fmac_f32_e32 v21, v58, v84
	v_fmac_f32_e32 v20, v58, v112
	v_fmac_f32_e32 v19, v58, v86
	v_fmac_f32_e32 v22, v60, v83
	v_fmac_f32_e32 v17, v60, v84
	v_fmac_f32_e32 v16, v60, v112
	v_fmac_f32_e32 v15, v60, v86
	v_fmac_f32_e32 v18, v65, v84
	v_fmac_f32_e32 v14, v65, v112
	v_fmac_f32_e32 v13, v67, v112
	v_fmac_f32_e32 v30, v58, v107
	v_fmac_f32_e32 v25, v58, v82
	v_fmac_f32_e32 v24, v56, v82
	v_fmac_f32_e32 v23, v56, v110
	v_fmac_f32_e32 v26, v56, v85
	v_fmac_f32_e32 v21, v56, v83
	v_fmac_f32_e32 v20, v56, v84
	v_fmac_f32_e32 v19, v56, v112
	v_fmac_f32_e32 v22, v62, v85
	v_fmac_f32_e32 v17, v62, v83
	v_fmac_f32_e32 v16, v62, v84
	v_fmac_f32_e32 v15, v62, v112
	v_fmac_f32_e32 v18, v67, v83
	v_fmac_f32_e32 v14, v67, v84
	v_fmac_f32_e32 v13, v68, v84
	v_fmac_f32_e32 v30, v56, v105
	v_fmac_f32_e32 v25, v56, v107
	v_fmac_f32_e32 v24, v57, v107
	v_fmac_f32_e32 v23, v57, v82
	v_fmac_f32_e32 v26, v57, v110
	v_fmac_f32_e32 v21, v57, v85
	v_fmac_f32_e32 v20, v57, v83
	v_fmac_f32_e32 v19, v57, v84
	v_fmac_f32_e32 v22, v64, v110
	v_fmac_f32_e32 v17, v64, v85
	v_fmac_f32_e32 v16, v64, v83
	v_fmac_f32_e32 v15, v64, v84
	v_fmac_f32_e32 v18, v68, v85
	v_fmac_f32_e32 v14, v68, v83
	v_fmac_f32_e32 v13, v70, v83
	v_fmac_f32_e32 v30, v57, v109
	v_fmac_f32_e32 v25, v57, v105
	v_fmac_f32_e32 v24, v59, v105
	v_fmac_f32_e32 v23, v59, v107
	v_fmac_f32_e32 v26, v59, v82
	v_fmac_f32_e32 v21, v59, v110
	v_fmac_f32_e32 v20, v59, v85
	v_fmac_f32_e32 v19, v59, v83
	v_fmac_f32_e32 v22, v65, v82
	v_fmac_f32_e32 v17, v65, v110
	v_fmac_f32_e32 v16, v65, v85
	v_fmac_f32_e32 v15, v65, v83
	v_fmac_f32_e32 v18, v70, v110
	v_fmac_f32_e32 v14, v70, v85
	v_fmac_f32_e32 v13, v72, v85
	v_fmac_f32_e32 v27, v111, v89
	v_fmac_f32_e32 v30, v59, v102
	v_fmac_f32_e32 v25, v59, v109
	v_fmac_f32_e32 v24, v60, v109
	v_fmac_f32_e32 v23, v60, v105
	v_fmac_f32_e32 v26, v60, v107
	v_fmac_f32_e32 v21, v60, v82
	v_fmac_f32_e32 v20, v60, v110
	v_fmac_f32_e32 v19, v60, v85
	v_fmac_f32_e32 v22, v67, v107
	v_fmac_f32_e32 v17, v67, v82
	v_fmac_f32_e32 v16, v67, v110
	v_fmac_f32_e32 v15, v67, v85
	v_fmac_f32_e32 v18, v72, v82
	v_fmac_f32_e32 v14, v72, v110
	v_fmac_f32_e32 v13, v73, v110
	v_fmac_f32_e32 v54, v111, v101
	v_fmac_f32_e32 v53, v111, v102
	v_fmac_f32_e32 v52, v111, v109
	v_fmac_f32_e32 v44, v111, v105
	v_fmac_f32_e32 v47, v111, v107
	v_fmac_f32_e32 v36, v111, v82
	v_fmac_f32_e32 v37, v111, v110
	v_fmac_f32_e32 v38, v111, v85
	v_fmac_f32_e32 v41, v111, v83
	v_fmac_f32_e32 v34, v111, v84
	v_fmac_f32_e32 v32, v111, v112
	v_fmac_f32_e32 v31, v111, v86
	v_fmac_f32_e32 v33, v111, v87
	v_fmac_f32_e32 v29, v111, v88
	v_fmac_f32_e32 v28, v111, v78
	v_fmac_f32_e32 v27, v91, v78
	v_fmac_f32_e32 v30, v60, v101
	v_fmac_f32_e32 v25, v60, v102
	v_fmac_f32_e32 v24, v62, v102
	v_fmac_f32_e32 v23, v62, v109
	v_fmac_f32_e32 v26, v62, v105
	v_fmac_f32_e32 v21, v62, v107
	v_fmac_f32_e32 v20, v62, v82
	v_fmac_f32_e32 v19, v62, v110
	v_fmac_f32_e32 v22, v68, v105
	v_fmac_f32_e32 v17, v68, v107
	v_fmac_f32_e32 v16, v68, v82
	v_fmac_f32_e32 v15, v68, v110
	v_fmac_f32_e32 v18, v73, v107
	v_fmac_f32_e32 v14, v73, v82
	v_fmac_f32_e32 v13, v75, v82
	v_fmac_f32_e32 v54, v91, v98
	v_fmac_f32_e32 v53, v91, v101
	v_fmac_f32_e32 v52, v91, v102
	v_fmac_f32_e32 v44, v91, v109
	v_fmac_f32_e32 v47, v91, v105
	v_fmac_f32_e32 v36, v91, v107
	v_fmac_f32_e32 v37, v91, v82
	v_fmac_f32_e32 v38, v91, v110
	v_fmac_f32_e32 v41, v91, v85
	v_fmac_f32_e32 v34, v91, v83
	v_fmac_f32_e32 v32, v91, v84
	v_fmac_f32_e32 v31, v91, v112
	v_fmac_f32_e32 v33, v91, v86
	v_fmac_f32_e32 v29, v91, v87
	v_fmac_f32_e32 v28, v91, v88
	v_fmac_f32_e32 v27, v90, v88
	v_fmac_f32_e32 v30, v62, v98
	v_fmac_f32_e32 v25, v62, v101
	v_fmac_f32_e32 v24, v64, v101
	v_fmac_f32_e32 v23, v64, v102
	v_fmac_f32_e32 v26, v64, v109
	v_fmac_f32_e32 v21, v64, v105
	v_fmac_f32_e32 v20, v64, v107
	v_fmac_f32_e32 v19, v64, v82
	v_fmac_f32_e32 v22, v70, v109
	v_fmac_f32_e32 v17, v70, v105
	v_fmac_f32_e32 v16, v70, v107
	v_fmac_f32_e32 v15, v70, v82
	v_fmac_f32_e32 v18, v75, v105
	v_fmac_f32_e32 v14, v75, v107
	v_fmac_f32_e32 v13, v115, v107
	s_waitcnt vmcnt(8)
; __device__ __forceinline__ void conv_tile(const Params& p, int l, int item, const bf16* PROJ, bf16* CV, LAS float* sl) {
;     ...
;     for (int t = 0; t < 32; ++t) { float acc = bias;
; #pragma unroll
;         for (int j = 0; j < 31; ++j) acc = fmaf(u[t + j], w[j], acc);
;         y[t] = acc; y2[t] = acc * acc; }
	v_fmac_f32_e32 v54, v90, v108
	v_fmac_f32_e32 v53, v90, v98
	v_fmac_f32_e32 v52, v90, v101
	v_fmac_f32_e32 v44, v90, v102
	v_fmac_f32_e32 v47, v90, v109
	v_fmac_f32_e32 v36, v90, v105
	v_fmac_f32_e32 v37, v90, v107
	v_fmac_f32_e32 v38, v90, v82
	v_fmac_f32_e32 v41, v90, v110
	v_fmac_f32_e32 v34, v90, v85
	v_fmac_f32_e32 v32, v90, v83
	v_fmac_f32_e32 v31, v90, v84
	v_fmac_f32_e32 v33, v90, v112
	v_fmac_f32_e32 v29, v90, v86
	v_fmac_f32_e32 v28, v90, v87
	v_fmac_f32_e32 v27, v81, v87
	v_fmac_f32_e32 v30, v64, v108
	v_fmac_f32_e32 v25, v64, v98
	v_fmac_f32_e32 v24, v65, v98
	v_fmac_f32_e32 v23, v65, v101
	v_fmac_f32_e32 v26, v65, v102
	v_fmac_f32_e32 v21, v65, v109
	v_fmac_f32_e32 v20, v65, v105
	v_fmac_f32_e32 v19, v65, v107
	v_fmac_f32_e32 v22, v72, v102
	v_fmac_f32_e32 v17, v72, v109
	v_fmac_f32_e32 v16, v72, v105
	v_fmac_f32_e32 v15, v72, v107
	v_fmac_f32_e32 v18, v115, v109
	v_fmac_f32_e32 v14, v115, v105
	v_fmac_f32_e32 v13, v116, v105
	v_fmac_f32_e32 v54, v81, v94
	v_fmac_f32_e32 v53, v81, v108
	v_fmac_f32_e32 v52, v81, v98
	v_fmac_f32_e32 v44, v81, v101
	v_fmac_f32_e32 v47, v81, v102
	v_fmac_f32_e32 v36, v81, v109
	v_fmac_f32_e32 v37, v81, v105
	v_fmac_f32_e32 v38, v81, v107
	v_fmac_f32_e32 v41, v81, v82
	v_fmac_f32_e32 v34, v81, v110
	v_fmac_f32_e32 v32, v81, v85
	v_fmac_f32_e32 v31, v81, v83
	v_fmac_f32_e32 v33, v81, v84
	v_fmac_f32_e32 v29, v81, v112
	v_fmac_f32_e32 v28, v81, v86
	v_fmac_f32_e32 v27, v77, v86
	v_fmac_f32_e32 v30, v65, v94
	v_fmac_f32_e32 v25, v65, v108
	v_fmac_f32_e32 v24, v67, v108
	v_fmac_f32_e32 v23, v67, v98
	v_fmac_f32_e32 v26, v67, v101
	v_fmac_f32_e32 v21, v67, v102
	v_fmac_f32_e32 v20, v67, v109
	v_fmac_f32_e32 v19, v67, v105
	v_fmac_f32_e32 v22, v73, v101
	v_fmac_f32_e32 v17, v73, v102
	v_fmac_f32_e32 v16, v73, v109
	v_fmac_f32_e32 v15, v73, v105
	v_fmac_f32_e32 v18, v116, v102
	v_fmac_f32_e32 v14, v116, v109
	v_fmac_f32_e32 v13, v117, v109
	v_fmac_f32_e32 v54, v77, v93
	v_fmac_f32_e32 v53, v77, v94
	v_fmac_f32_e32 v52, v77, v108
	v_fmac_f32_e32 v44, v77, v98
	v_fmac_f32_e32 v47, v77, v101
	v_fmac_f32_e32 v36, v77, v102
	v_fmac_f32_e32 v37, v77, v109
	v_fmac_f32_e32 v38, v77, v105
	v_fmac_f32_e32 v41, v77, v107
	v_fmac_f32_e32 v34, v77, v82
	v_fmac_f32_e32 v32, v77, v110
	v_fmac_f32_e32 v31, v77, v85
	v_fmac_f32_e32 v33, v77, v83
	v_fmac_f32_e32 v29, v77, v84
	v_fmac_f32_e32 v28, v77, v112
	v_fmac_f32_e32 v27, v76, v112
	v_fmac_f32_e32 v30, v67, v93
	v_fmac_f32_e32 v25, v67, v94
	v_fmac_f32_e32 v24, v68, v94
	v_fmac_f32_e32 v23, v68, v108
	v_fmac_f32_e32 v26, v68, v98
	v_fmac_f32_e32 v21, v68, v101
	v_fmac_f32_e32 v20, v68, v102
	v_fmac_f32_e32 v19, v68, v109
	v_fmac_f32_e32 v22, v75, v98
	v_fmac_f32_e32 v17, v75, v101
	v_fmac_f32_e32 v16, v75, v102
	v_fmac_f32_e32 v15, v75, v109
	v_fmac_f32_e32 v18, v117, v101
	v_fmac_f32_e32 v14, v117, v102
	v_fmac_f32_e32 v13, v6, v102
	v_fmac_f32_e32 v54, v76, v92
	v_fmac_f32_e32 v53, v76, v93
	v_fmac_f32_e32 v52, v76, v94
	v_fmac_f32_e32 v44, v76, v108
	v_fmac_f32_e32 v47, v76, v98
	v_fmac_f32_e32 v36, v76, v101
	v_fmac_f32_e32 v37, v76, v102
	v_fmac_f32_e32 v38, v76, v109
	v_fmac_f32_e32 v41, v76, v105
	v_fmac_f32_e32 v34, v76, v107
	v_fmac_f32_e32 v32, v76, v82
	v_fmac_f32_e32 v31, v76, v110
	v_fmac_f32_e32 v33, v76, v85
	v_fmac_f32_e32 v29, v76, v83
	v_fmac_f32_e32 v28, v76, v84
	v_fmac_f32_e32 v27, v74, v84
	v_fmac_f32_e32 v30, v68, v92
	v_fmac_f32_e32 v25, v68, v93
	v_fmac_f32_e32 v24, v70, v93
	v_fmac_f32_e32 v23, v70, v94
	v_fmac_f32_e32 v26, v70, v108
	v_fmac_f32_e32 v21, v70, v98
	v_fmac_f32_e32 v20, v70, v101
	v_fmac_f32_e32 v19, v70, v102
	v_fmac_f32_e32 v22, v115, v108
	v_fmac_f32_e32 v17, v115, v98
	v_fmac_f32_e32 v16, v115, v101
	v_fmac_f32_e32 v15, v115, v102
	v_fmac_f32_e32 v18, v6, v98
	v_fmac_f32_e32 v14, v6, v101
	v_fmac_f32_e32 v13, v8, v101
	s_waitcnt vmcnt(7)
	v_fmac_f32_e32 v54, v74, v96
	v_fmac_f32_e32 v53, v74, v92
	v_fmac_f32_e32 v52, v74, v93
	v_fmac_f32_e32 v44, v74, v94
	v_fmac_f32_e32 v47, v74, v108
	v_fmac_f32_e32 v36, v74, v98
	v_fmac_f32_e32 v37, v74, v101
	v_fmac_f32_e32 v38, v74, v102
	v_fmac_f32_e32 v41, v74, v109
	v_fmac_f32_e32 v34, v74, v105
	v_fmac_f32_e32 v32, v74, v107
	v_fmac_f32_e32 v31, v74, v82
	v_fmac_f32_e32 v33, v74, v110
	v_fmac_f32_e32 v29, v74, v85
	v_fmac_f32_e32 v28, v74, v83
	v_fmac_f32_e32 v27, v71, v83
	v_fmac_f32_e32 v30, v70, v96
	v_fmac_f32_e32 v25, v70, v92
	v_fmac_f32_e32 v24, v72, v92
	v_fmac_f32_e32 v23, v72, v93
	v_fmac_f32_e32 v26, v72, v94
	v_fmac_f32_e32 v21, v72, v108
	v_fmac_f32_e32 v20, v72, v98
	v_fmac_f32_e32 v19, v72, v101
	v_fmac_f32_e32 v22, v116, v94
	v_fmac_f32_e32 v17, v116, v108
	v_fmac_f32_e32 v16, v116, v98
	v_fmac_f32_e32 v15, v116, v101
	v_fmac_f32_e32 v18, v8, v108
	v_fmac_f32_e32 v14, v8, v98
	v_fmac_f32_e32 v13, v7, v98
	s_waitcnt vmcnt(5)
	v_fmac_f32_e32 v54, v71, v106
	v_fmac_f32_e32 v53, v71, v96
	v_fmac_f32_e32 v52, v71, v92
	v_fmac_f32_e32 v44, v71, v93
	v_fmac_f32_e32 v47, v71, v94
	v_fmac_f32_e32 v36, v71, v108
	v_fmac_f32_e32 v37, v71, v98
	v_fmac_f32_e32 v38, v71, v101
	v_fmac_f32_e32 v41, v71, v102
	v_fmac_f32_e32 v34, v71, v109
	v_fmac_f32_e32 v32, v71, v105
	v_fmac_f32_e32 v31, v71, v107
	v_fmac_f32_e32 v33, v71, v82
	v_fmac_f32_e32 v29, v71, v110
	v_fmac_f32_e32 v28, v71, v85
	v_fmac_f32_e32 v27, v69, v85
	v_fmac_f32_e32 v30, v72, v106
	v_fmac_f32_e32 v25, v72, v96
	v_fmac_f32_e32 v24, v73, v96
	v_fmac_f32_e32 v23, v73, v92
	v_fmac_f32_e32 v26, v73, v93
	v_fmac_f32_e32 v21, v73, v94
	v_fmac_f32_e32 v20, v73, v108
	v_fmac_f32_e32 v19, v73, v98
	v_fmac_f32_e32 v22, v117, v93
	v_fmac_f32_e32 v17, v117, v94
	v_fmac_f32_e32 v16, v117, v108
	v_fmac_f32_e32 v15, v117, v98
	v_fmac_f32_e32 v18, v7, v94
	v_fmac_f32_e32 v14, v7, v108
	v_fmac_f32_e32 v13, v35, v108
	v_fmac_f32_e32 v55, v111, v98
	s_waitcnt vmcnt(4)
; __device__ __forceinline__ void conv_tile(const Params& p, int l, int item, const bf16* PROJ, bf16* CV, LAS float* sl) {
;     ...
;     for (int t = 0; t < 32; ++t) { float acc = bias;
; #pragma unroll
;         for (int j = 0; j < 31; ++j) acc = fmaf(u[t + j], w[j], acc);
;         y[t] = acc; y2[t] = acc * acc; }
	v_fmac_f32_e32 v54, v69, v104
	v_fmac_f32_e32 v53, v69, v106
	v_fmac_f32_e32 v52, v69, v96
	v_fmac_f32_e32 v44, v69, v92
	v_fmac_f32_e32 v47, v69, v93
	v_fmac_f32_e32 v36, v69, v94
	v_fmac_f32_e32 v37, v69, v108
	v_fmac_f32_e32 v38, v69, v98
	v_fmac_f32_e32 v41, v69, v101
	v_fmac_f32_e32 v34, v69, v102
	v_fmac_f32_e32 v32, v69, v109
	v_fmac_f32_e32 v31, v69, v105
	v_fmac_f32_e32 v33, v69, v107
	v_fmac_f32_e32 v29, v69, v82
	v_fmac_f32_e32 v28, v69, v110
	v_fmac_f32_e32 v27, v66, v110
	v_fmac_f32_e32 v30, v73, v104
	v_fmac_f32_e32 v25, v73, v106
	v_fmac_f32_e32 v24, v75, v106
	v_fmac_f32_e32 v23, v75, v96
	v_fmac_f32_e32 v26, v75, v92
	v_fmac_f32_e32 v21, v75, v93
	v_fmac_f32_e32 v20, v75, v94
	v_fmac_f32_e32 v19, v75, v108
	v_fmac_f32_e32 v22, v6, v92
	v_fmac_f32_e32 v17, v6, v93
	v_fmac_f32_e32 v16, v6, v94
	v_fmac_f32_e32 v15, v6, v108
	v_fmac_f32_e32 v18, v35, v93
	v_fmac_f32_e32 v14, v35, v94
	v_fmac_f32_e32 v13, v9, v94
	v_fmac_f32_e32 v55, v91, v108
	s_waitcnt vmcnt(3)
	v_fmac_f32_e32 v54, v66, v103
	v_fmac_f32_e32 v53, v66, v104
	v_fmac_f32_e32 v52, v66, v106
	v_fmac_f32_e32 v44, v66, v96
	v_fmac_f32_e32 v47, v66, v92
	v_fmac_f32_e32 v36, v66, v93
	v_fmac_f32_e32 v37, v66, v94
	v_fmac_f32_e32 v38, v66, v108
	v_fmac_f32_e32 v41, v66, v98
	v_fmac_f32_e32 v34, v66, v101
	v_fmac_f32_e32 v32, v66, v102
	v_fmac_f32_e32 v31, v66, v109
	v_fmac_f32_e32 v33, v66, v105
	v_fmac_f32_e32 v29, v66, v107
	v_fmac_f32_e32 v28, v66, v82
	v_fmac_f32_e32 v27, v63, v82
	v_fmac_f32_e32 v30, v75, v103
	v_fmac_f32_e32 v25, v75, v104
	v_fmac_f32_e32 v24, v115, v104
	v_fmac_f32_e32 v23, v115, v106
	v_fmac_f32_e32 v26, v115, v96
	v_fmac_f32_e32 v21, v115, v92
	v_fmac_f32_e32 v20, v115, v93
	v_fmac_f32_e32 v19, v115, v94
	v_fmac_f32_e32 v22, v8, v96
	v_fmac_f32_e32 v17, v8, v92
	v_fmac_f32_e32 v16, v8, v93
	v_fmac_f32_e32 v15, v8, v94
	v_fmac_f32_e32 v18, v9, v92
	v_fmac_f32_e32 v14, v9, v93
	v_fmac_f32_e32 v13, v40, v93
	v_fmac_f32_e32 v55, v90, v94
	v_fmac_f32_e32 v54, v63, v95
	v_fmac_f32_e32 v53, v63, v103
	v_fmac_f32_e32 v52, v63, v104
	v_fmac_f32_e32 v44, v63, v106
	v_fmac_f32_e32 v47, v63, v96
	v_fmac_f32_e32 v36, v63, v92
	v_fmac_f32_e32 v37, v63, v93
	v_fmac_f32_e32 v38, v63, v94
	v_fmac_f32_e32 v41, v63, v108
	v_fmac_f32_e32 v34, v63, v98
	v_fmac_f32_e32 v32, v63, v101
	v_fmac_f32_e32 v31, v63, v102
	v_fmac_f32_e32 v33, v63, v109
	v_fmac_f32_e32 v29, v63, v105
	v_fmac_f32_e32 v28, v63, v107
	v_fmac_f32_e32 v27, v61, v107
	v_fmac_f32_e32 v30, v115, v95
	v_fmac_f32_e32 v25, v115, v103
	v_fmac_f32_e32 v24, v116, v103
	v_fmac_f32_e32 v23, v116, v104
	v_fmac_f32_e32 v26, v116, v106
	v_fmac_f32_e32 v21, v116, v96
	v_fmac_f32_e32 v20, v116, v92
	v_fmac_f32_e32 v19, v116, v93
	v_fmac_f32_e32 v22, v7, v106
	v_fmac_f32_e32 v17, v7, v96
	v_fmac_f32_e32 v16, v7, v92
	v_fmac_f32_e32 v15, v7, v93
	v_fmac_f32_e32 v18, v40, v96
	v_fmac_f32_e32 v14, v40, v92
	v_fmac_f32_e32 v13, v39, v92
	v_fmac_f32_e32 v55, v81, v93
	s_waitcnt vmcnt(2)
	v_fmac_f32_e32 v54, v61, v99
	v_fmac_f32_e32 v53, v61, v95
	v_fmac_f32_e32 v52, v61, v103
	v_fmac_f32_e32 v44, v61, v104
	v_fmac_f32_e32 v47, v61, v106
	v_fmac_f32_e32 v36, v61, v96
	v_fmac_f32_e32 v37, v61, v92
	v_fmac_f32_e32 v38, v61, v93
	v_fmac_f32_e32 v41, v61, v94
	v_fmac_f32_e32 v34, v61, v108
	v_fmac_f32_e32 v32, v61, v98
	v_fmac_f32_e32 v31, v61, v101
	v_fmac_f32_e32 v33, v61, v102
	v_fmac_f32_e32 v29, v61, v109
	v_fmac_f32_e32 v28, v61, v105
	v_fmac_f32_e32 v27, v58, v105
	v_fmac_f32_e32 v30, v116, v99
	v_fmac_f32_e32 v25, v116, v95
	v_fmac_f32_e32 v24, v117, v95
	v_fmac_f32_e32 v23, v117, v103
	v_fmac_f32_e32 v26, v117, v104
	v_fmac_f32_e32 v21, v117, v106
	v_fmac_f32_e32 v20, v117, v96
	v_fmac_f32_e32 v19, v117, v92
	v_fmac_f32_e32 v22, v35, v104
	v_fmac_f32_e32 v17, v35, v106
	v_fmac_f32_e32 v16, v35, v96
	v_fmac_f32_e32 v15, v35, v92
	v_fmac_f32_e32 v18, v39, v106
	v_fmac_f32_e32 v14, v39, v96
	v_fmac_f32_e32 v13, v43, v96
	v_fmac_f32_e32 v55, v77, v92
	s_waitcnt vmcnt(1)
	v_fmac_f32_e32 v54, v58, v97
	v_fmac_f32_e32 v53, v58, v99
	v_fmac_f32_e32 v52, v58, v95
	v_fmac_f32_e32 v44, v58, v103
	v_fmac_f32_e32 v47, v58, v104
	v_fmac_f32_e32 v36, v58, v106
	v_fmac_f32_e32 v37, v58, v96
	v_fmac_f32_e32 v38, v58, v92
	v_fmac_f32_e32 v41, v58, v93
	v_fmac_f32_e32 v34, v58, v94
	v_fmac_f32_e32 v32, v58, v108
	v_fmac_f32_e32 v31, v58, v98
	v_fmac_f32_e32 v33, v58, v101
	v_fmac_f32_e32 v29, v58, v102
	v_fmac_f32_e32 v28, v58, v109
	v_fmac_f32_e32 v27, v56, v109
	v_fmac_f32_e32 v30, v117, v97
	v_fmac_f32_e32 v25, v117, v99
	v_fmac_f32_e32 v24, v6, v99
	v_fmac_f32_e32 v23, v6, v95
	v_fmac_f32_e32 v26, v6, v103
	v_fmac_f32_e32 v21, v6, v104
	v_fmac_f32_e32 v20, v6, v106
	v_fmac_f32_e32 v19, v6, v96
	v_fmac_f32_e32 v22, v9, v103
	v_fmac_f32_e32 v17, v9, v104
	v_fmac_f32_e32 v16, v9, v106
	v_fmac_f32_e32 v15, v9, v96
	v_fmac_f32_e32 v18, v43, v104
	v_fmac_f32_e32 v14, v43, v106
	v_fmac_f32_e32 v13, v42, v106
	v_fmac_f32_e32 v55, v76, v96
	s_waitcnt vmcnt(0)
; __device__ __forceinline__ float wave_reduce32(const float (&v)[32], int lane) {
;     float a[16], b[8], c[4], d[2], e;
;     { const bool h = lane & 32;
; #pragma unroll
;       for (int t = 0; t < 16; ++t) { const float keep = h ? v[t + 16] : v[t], send = h ? v[t] : v[t + 16]; a[t] = keep + __shfl_xor(send, 32); } }
; __device__ __forceinline__ void conv_tile(const Params& p, int l, int item, const bf16* PROJ, bf16* CV, LAS float* sl) {
;     ...
;     for (int t = 0; t < 32; ++t) { float acc = bias;
; #pragma unroll
;         for (int j = 0; j < 31; ++j) acc = fmaf(u[t + j], w[j], acc);
;         y[t] = acc; y2[t] = acc * acc; }
;     const float r1 = wave_reduce32(y, lane), r2 = wave_reduce32(y2, lane);
	v_fmac_f32_e32 v54, v56, v100
	v_fmac_f32_e32 v53, v56, v97
	v_fmac_f32_e32 v52, v56, v99
	v_fmac_f32_e32 v44, v56, v95
	v_fmac_f32_e32 v47, v56, v103
	v_fmac_f32_e32 v36, v56, v104
	v_fmac_f32_e32 v37, v56, v106
	v_fmac_f32_e32 v38, v56, v96
	v_fmac_f32_e32 v41, v56, v92
	v_fmac_f32_e32 v34, v56, v93
	v_fmac_f32_e32 v32, v56, v94
	v_fmac_f32_e32 v31, v56, v108
	v_fmac_f32_e32 v33, v56, v98
	v_fmac_f32_e32 v29, v56, v101
	v_fmac_f32_e32 v28, v56, v102
	v_fmac_f32_e32 v27, v57, v102
	v_fmac_f32_e32 v30, v6, v100
	v_fmac_f32_e32 v25, v6, v97
	v_fmac_f32_e32 v24, v8, v97
	v_fmac_f32_e32 v23, v8, v99
	v_fmac_f32_e32 v26, v8, v95
	v_fmac_f32_e32 v21, v8, v103
	v_fmac_f32_e32 v20, v8, v104
	v_fmac_f32_e32 v19, v8, v106
	v_fmac_f32_e32 v22, v40, v95
	v_fmac_f32_e32 v17, v40, v103
	v_fmac_f32_e32 v16, v40, v104
	v_fmac_f32_e32 v15, v40, v106
	v_fmac_f32_e32 v18, v42, v103
	v_fmac_f32_e32 v14, v42, v104
	v_fmac_f32_e32 v13, v46, v104
	v_cmp_eq_u32_e64 s[0:1], 0, v114
	v_fmac_f32_e32 v55, v74, v106
	v_fmac_f32_e32 v53, v57, v100
	v_fmac_f32_e32 v52, v57, v97
	v_fmac_f32_e32 v44, v57, v99
	v_fmac_f32_e32 v47, v57, v95
	v_fmac_f32_e32 v36, v57, v103
	v_fmac_f32_e32 v37, v57, v104
	v_fmac_f32_e32 v38, v57, v106
	v_fmac_f32_e32 v41, v57, v96
	v_fmac_f32_e32 v34, v57, v92
	v_fmac_f32_e32 v32, v57, v93
	v_fmac_f32_e32 v31, v57, v94
	v_fmac_f32_e32 v33, v57, v108
	v_fmac_f32_e32 v29, v57, v98
	v_fmac_f32_e32 v28, v57, v101
	v_fmac_f32_e32 v27, v59, v101
	v_fmac_f32_e32 v25, v8, v100
	v_fmac_f32_e32 v24, v7, v100
	v_fmac_f32_e32 v23, v7, v97
	v_fmac_f32_e32 v26, v7, v99
	v_fmac_f32_e32 v21, v7, v95
	v_fmac_f32_e32 v20, v7, v103
	v_fmac_f32_e32 v19, v7, v104
	v_fmac_f32_e32 v22, v39, v99
	v_fmac_f32_e32 v17, v39, v95
	v_fmac_f32_e32 v16, v39, v103
	v_fmac_f32_e32 v15, v39, v104
	v_fmac_f32_e32 v18, v46, v95
	v_fmac_f32_e32 v14, v46, v103
	v_fmac_f32_e32 v13, v45, v103
	v_cndmask_b32_e64 v7, v54, v30, s[0:1]
	v_fmac_f32_e32 v55, v71, v104
	v_fmac_f32_e32 v52, v59, v100
	v_fmac_f32_e32 v44, v59, v97
	v_fmac_f32_e32 v47, v59, v99
	v_fmac_f32_e32 v36, v59, v95
	v_fmac_f32_e32 v37, v59, v103
	v_fmac_f32_e32 v38, v59, v104
	v_fmac_f32_e32 v41, v59, v106
	v_fmac_f32_e32 v34, v59, v96
	v_fmac_f32_e32 v32, v59, v92
	v_fmac_f32_e32 v31, v59, v93
	v_fmac_f32_e32 v33, v59, v94
	v_fmac_f32_e32 v29, v59, v108
	v_fmac_f32_e32 v28, v59, v98
	v_fmac_f32_e32 v27, v60, v98
	v_fmac_f32_e32 v22, v43, v97
	v_fmac_f32_e32 v17, v43, v99
	v_fmac_f32_e32 v16, v43, v95
	v_fmac_f32_e32 v15, v43, v103
	v_fmac_f32_e32 v18, v45, v99
	v_fmac_f32_e32 v14, v45, v95
	v_fmac_f32_e32 v13, v49, v95
	ds_bpermute_b32 v8, v186, v7
	v_cndmask_b32_e64 v7, v53, v25, s[0:1]
	v_fmac_f32_e32 v55, v69, v103
	v_fmac_f32_e32 v44, v60, v100
	v_fmac_f32_e32 v47, v60, v97
	v_fmac_f32_e32 v36, v60, v99
	v_fmac_f32_e32 v37, v60, v95
	v_fmac_f32_e32 v38, v60, v103
	v_fmac_f32_e32 v41, v60, v104
	v_fmac_f32_e32 v34, v60, v106
	v_fmac_f32_e32 v32, v60, v96
	v_fmac_f32_e32 v31, v60, v92
	v_fmac_f32_e32 v33, v60, v93
	v_fmac_f32_e32 v29, v60, v94
	v_fmac_f32_e32 v28, v60, v108
	v_fmac_f32_e32 v27, v62, v108
	v_fmac_f32_e32 v23, v35, v100
	v_fmac_f32_e32 v26, v35, v97
	v_fmac_f32_e32 v21, v35, v99
	v_fmac_f32_e32 v20, v35, v95
	v_fmac_f32_e32 v19, v35, v103
	v_fmac_f32_e32 v22, v42, v100
	v_fmac_f32_e32 v17, v42, v97
	v_fmac_f32_e32 v16, v42, v99
	v_fmac_f32_e32 v15, v42, v95
	v_fmac_f32_e32 v18, v49, v97
	v_fmac_f32_e32 v14, v49, v99
	v_fmac_f32_e32 v13, v48, v99
	ds_bpermute_b32 v42, v186, v7
	v_cndmask_b32_e64 v7, v52, v24, s[0:1]
	v_fmac_f32_e32 v55, v66, v95
	v_fmac_f32_e32 v47, v62, v100
	v_fmac_f32_e32 v36, v62, v97
	v_fmac_f32_e32 v37, v62, v99
	v_fmac_f32_e32 v38, v62, v95
	v_fmac_f32_e32 v41, v62, v103
	v_fmac_f32_e32 v34, v62, v104
	v_fmac_f32_e32 v32, v62, v106
	v_fmac_f32_e32 v31, v62, v96
	v_fmac_f32_e32 v33, v62, v92
	v_fmac_f32_e32 v29, v62, v93
	v_fmac_f32_e32 v28, v62, v94
	v_fmac_f32_e32 v27, v64, v94
	v_fmac_f32_e32 v26, v9, v100
	v_fmac_f32_e32 v21, v9, v97
	v_fmac_f32_e32 v20, v9, v99
	v_fmac_f32_e32 v19, v9, v95
	v_fmac_f32_e32 v18, v48, v100
	v_fmac_f32_e32 v14, v48, v97
	v_fmac_f32_e32 v13, v51, v97
	ds_bpermute_b32 v48, v186, v7
	v_cndmask_b32_e64 v7, v44, v23, s[0:1]
	v_fmac_f32_e32 v55, v63, v99
	v_fmac_f32_e32 v36, v64, v100
	v_fmac_f32_e32 v37, v64, v97
	v_fmac_f32_e32 v38, v64, v99
	v_fmac_f32_e32 v41, v64, v95
	v_fmac_f32_e32 v34, v64, v103
	v_fmac_f32_e32 v32, v64, v104
	v_fmac_f32_e32 v31, v64, v106
	v_fmac_f32_e32 v33, v64, v96
	v_fmac_f32_e32 v29, v64, v92
	v_fmac_f32_e32 v28, v64, v93
	v_fmac_f32_e32 v27, v65, v93
	v_fmac_f32_e32 v21, v40, v100
	v_fmac_f32_e32 v20, v40, v97
	v_fmac_f32_e32 v19, v40, v99
	v_fmac_f32_e32 v13, v50, v100
	ds_bpermute_b32 v50, v186, v7
	v_cndmask_b32_e64 v7, v47, v26, s[0:1]
	v_fmac_f32_e32 v55, v61, v97
	v_fmac_f32_e32 v37, v65, v100
	v_fmac_f32_e32 v38, v65, v97
	v_fmac_f32_e32 v41, v65, v99
	v_fmac_f32_e32 v34, v65, v95
	v_fmac_f32_e32 v32, v65, v103
	v_fmac_f32_e32 v31, v65, v104
	v_fmac_f32_e32 v33, v65, v106
	v_fmac_f32_e32 v29, v65, v96
	v_fmac_f32_e32 v28, v65, v92
	v_fmac_f32_e32 v27, v67, v92
	v_fmac_f32_e32 v20, v39, v100
	v_fmac_f32_e32 v19, v39, v97
	ds_bpermute_b32 v56, v186, v7
	v_cndmask_b32_e64 v7, v36, v21, s[0:1]
	v_fmac_f32_e32 v55, v58, v100
	v_fmac_f32_e32 v38, v67, v100
	v_fmac_f32_e32 v41, v67, v97
	v_fmac_f32_e32 v34, v67, v99
	v_fmac_f32_e32 v32, v67, v95
	v_fmac_f32_e32 v31, v67, v103
	v_fmac_f32_e32 v33, v67, v104
	v_fmac_f32_e32 v29, v67, v106
	v_fmac_f32_e32 v28, v67, v96
	v_fmac_f32_e32 v27, v68, v96
	v_fmac_f32_e32 v19, v43, v100
	ds_bpermute_b32 v58, v186, v7
	v_cndmask_b32_e64 v7, v37, v20, s[0:1]
	v_fmac_f32_e32 v41, v68, v100
; __device__ __forceinline__ float wave_reduce32(const float (&v)[32], int lane) {
;     float a[16], b[8], c[4], d[2], e;
;     { const bool h = lane & 32;
; #pragma unroll
;       for (int t = 0; t < 16; ++t) { const float keep = h ? v[t + 16] : v[t], send = h ? v[t] : v[t + 16]; a[t] = keep + __shfl_xor(send, 32); } }
;     { const bool h = lane & 16;
; #pragma unroll
;       for (int t = 0; t < 8; ++t) { const float keep = h ? a[t + 8] : a[t], send = h ? a[t] : a[t + 8]; b[t] = keep + __shfl_xor(send, 16); } }
;     { const bool h = lane & 8;
; #pragma unroll
;       for (int t = 0; t < 4; ++t) { const float keep = h ? b[t + 4] : b[t], send = h ? b[t] : b[t + 4]; c[t] = keep + __shfl_xor(send, 8); } }
; __device__ __forceinline__ void conv_tile(const Params& p, int l, int item, const bf16* PROJ, bf16* CV, LAS float* sl) {
;     ...
;     for (int t = 0; t < 32; ++t) { float acc = bias;
; #pragma unroll
;         for (int j = 0; j < 31; ++j) acc = fmaf(u[t + j], w[j], acc);
;         y[t] = acc; y2[t] = acc * acc; }
	v_fmac_f32_e32 v34, v68, v97
	v_fmac_f32_e32 v32, v68, v99
	v_fmac_f32_e32 v31, v68, v95
	v_fmac_f32_e32 v33, v68, v103
	v_fmac_f32_e32 v29, v68, v104
	v_fmac_f32_e32 v28, v68, v106
	v_fmac_f32_e32 v27, v70, v106
	ds_bpermute_b32 v60, v186, v7
	v_cndmask_b32_e64 v7, v38, v19, s[0:1]
	v_fmac_f32_e32 v34, v70, v100
	v_fmac_f32_e32 v32, v70, v97
	v_fmac_f32_e32 v31, v70, v99
	v_fmac_f32_e32 v33, v70, v95
	v_fmac_f32_e32 v29, v70, v103
	v_fmac_f32_e32 v28, v70, v104
	v_fmac_f32_e32 v27, v72, v104
	v_fmac_f32_e32 v17, v46, v100
	v_fmac_f32_e32 v16, v46, v97
	v_fmac_f32_e32 v15, v46, v99
	ds_bpermute_b32 v62, v186, v7
	v_cndmask_b32_e64 v7, v41, v22, s[0:1]
	v_fmac_f32_e32 v32, v72, v100
	v_fmac_f32_e32 v31, v72, v97
	v_fmac_f32_e32 v33, v72, v99
	v_fmac_f32_e32 v29, v72, v95
	v_fmac_f32_e32 v28, v72, v103
	v_fmac_f32_e32 v27, v73, v103
	v_fmac_f32_e32 v16, v45, v100
	v_fmac_f32_e32 v15, v45, v97
	ds_bpermute_b32 v64, v186, v7
	v_cndmask_b32_e64 v7, v34, v17, s[0:1]
	v_fmac_f32_e32 v31, v73, v100
	v_fmac_f32_e32 v33, v73, v97
	v_fmac_f32_e32 v29, v73, v99
	v_fmac_f32_e32 v28, v73, v95
	v_fmac_f32_e32 v27, v75, v95
	v_fmac_f32_e32 v15, v49, v100
	ds_bpermute_b32 v66, v186, v7
	v_cndmask_b32_e64 v7, v32, v16, s[0:1]
	v_fmac_f32_e32 v33, v75, v100
	v_fmac_f32_e32 v29, v75, v97
	v_fmac_f32_e32 v28, v75, v99
	v_fmac_f32_e32 v27, v115, v99
	ds_bpermute_b32 v68, v186, v7
	v_cndmask_b32_e64 v7, v31, v15, s[0:1]
	v_fmac_f32_e32 v29, v115, v100
	v_fmac_f32_e32 v28, v115, v97
	v_fmac_f32_e32 v27, v116, v97
	v_fmac_f32_e32 v14, v51, v100
	ds_bpermute_b32 v70, v186, v7
	v_cndmask_b32_e64 v7, v33, v18, s[0:1]
	v_fmac_f32_e32 v28, v116, v100
	v_fmac_f32_e32 v27, v117, v100
	ds_bpermute_b32 v72, v186, v7
	v_cndmask_b32_e64 v7, v29, v14, s[0:1]
	v_mul_f32_e32 v113, v55, v55
	v_mul_f32_e32 v119, v27, v27
	ds_bpermute_b32 v78, v186, v7
	v_cndmask_b32_e64 v7, v28, v13, s[0:1]
	v_mul_f32_e32 v127, v38, v38
	v_mul_f32_e32 v74, v19, v19
	v_cndmask_b32_e64 v6, v55, v27, s[0:1]
	ds_bpermute_b32 v82, v186, v7
	v_cndmask_b32_e64 v7, v113, v119, s[0:1]
	v_mul_f32_e32 v118, v54, v54
	v_mul_f32_e32 v134, v30, v30
	ds_bpermute_b32 v6, v186, v6
	ds_bpermute_b32 v7, v186, v7
	v_cndmask_b32_e64 v63, v127, v74, s[0:1]
	v_mul_f32_e32 v128, v41, v41
	v_mul_f32_e32 v135, v22, v22
	v_cndmask_b32_e64 v9, v118, v134, s[0:1]
	ds_bpermute_b32 v63, v186, v63
	v_mul_f32_e32 v120, v53, v53
	v_mul_f32_e32 v133, v29, v29
	v_mul_f32_e32 v111, v25, v25
	v_mul_f32_e32 v140, v14, v14
	ds_bpermute_b32 v9, v186, v9
	v_cndmask_b32_e64 v65, v128, v135, s[0:1]
	v_mul_f32_e32 v122, v52, v52
	v_mul_f32_e32 v126, v37, v37
	v_mul_f32_e32 v129, v34, v34
	v_mul_f32_e32 v121, v28, v28
	v_mul_f32_e32 v91, v24, v24
	v_mul_f32_e32 v76, v20, v20
	v_mul_f32_e32 v136, v17, v17
	v_mul_f32_e32 v35, v13, v13
	v_cndmask_b32_e64 v43, v120, v111, s[0:1]
	ds_bpermute_b32 v65, v186, v65
	v_cndmask_b32_e64 v75, v133, v140, s[0:1]
	v_mul_f32_e32 v123, v44, v44
	v_mul_f32_e32 v130, v32, v32
	v_mul_f32_e32 v90, v23, v23
	v_mul_f32_e32 v137, v16, v16
	ds_bpermute_b32 v43, v186, v43
	v_cndmask_b32_e64 v49, v122, v91, s[0:1]
	v_cndmask_b32_e64 v61, v126, v76, s[0:1]
	v_cndmask_b32_e64 v67, v129, v136, s[0:1]
	ds_bpermute_b32 v79, v186, v75
	v_cndmask_b32_e64 v75, v121, v35, s[0:1]
	v_cndmask_b32_e64 v84, v27, v55, s[0:1]
	v_cndmask_b32_e64 v85, v119, v113, s[0:1]
	v_mul_f32_e32 v131, v31, v31
	v_mul_f32_e32 v138, v15, v15
	ds_bpermute_b32 v49, v186, v49
	v_cndmask_b32_e64 v51, v123, v90, s[0:1]
	ds_bpermute_b32 v61, v186, v61
	ds_bpermute_b32 v67, v186, v67
	v_cndmask_b32_e64 v69, v130, v137, s[0:1]
	ds_bpermute_b32 v83, v186, v75
	s_waitcnt lgkmcnt(9)
	v_pk_add_f32 v[6:7], v[84:85], v[6:7]
	v_cndmask_b32_e64 v84, v19, v38, s[0:1]
	v_cndmask_b32_e64 v85, v74, v127, s[0:1]
	ds_bpermute_b32 v51, v186, v51
	ds_bpermute_b32 v69, v186, v69
	v_cndmask_b32_e64 v71, v131, v138, s[0:1]
	s_waitcnt lgkmcnt(10)
	v_pk_add_f32 v[62:63], v[84:85], v[62:63]
	v_cndmask_b32_e64 v84, v30, v54, s[0:1]
	v_cndmask_b32_e64 v85, v134, v118, s[0:1]
	v_and_b32_e32 v39, 16, v2
	ds_bpermute_b32 v71, v186, v71
	s_waitcnt lgkmcnt(10)
	v_pk_add_f32 v[8:9], v[84:85], v[8:9]
	v_cndmask_b32_e64 v84, v22, v41, s[0:1]
	v_cndmask_b32_e64 v85, v135, v128, s[0:1]
	v_mul_f32_e32 v125, v36, v36
	v_mul_f32_e32 v77, v21, v21
	v_cmp_eq_u32_e32 vcc, 0, v39
	s_waitcnt lgkmcnt(9)
	v_pk_add_f32 v[64:65], v[84:85], v[64:65]
	v_cndmask_b32_e64 v84, v25, v53, s[0:1]
	v_cndmask_b32_e64 v85, v111, v120, s[0:1]
	v_cndmask_b32_e64 v59, v125, v77, s[0:1]
	v_cndmask_b32_e32 v39, v6, v62, vcc
	s_waitcnt lgkmcnt(8)
	v_pk_add_f32 v[42:43], v[84:85], v[42:43]
	v_cndmask_b32_e64 v84, v17, v34, s[0:1]
	v_cndmask_b32_e64 v85, v136, v129, s[0:1]
	v_cndmask_b32_e64 v86, v24, v52, s[0:1]
	v_cndmask_b32_e64 v87, v91, v122, s[0:1]
	v_cndmask_b32_e64 v93, v77, v125, s[0:1]
	v_cndmask_b32_e64 v94, v20, v37, s[0:1]
	v_cndmask_b32_e64 v95, v76, v126, s[0:1]
	v_cndmask_b32_e64 v76, v13, v28, s[0:1]
	v_cndmask_b32_e64 v77, v35, v121, s[0:1]
	ds_bpermute_b32 v74, v187, v39
	v_cndmask_b32_e32 v39, v8, v64, vcc
	s_waitcnt lgkmcnt(5)
	v_pk_add_f32 v[66:67], v[84:85], v[66:67]
	v_pk_add_f32 v[48:49], v[86:87], v[48:49]
	v_cndmask_b32_e64 v86, v16, v32, s[0:1]
	v_cndmask_b32_e64 v87, v137, v130, s[0:1]
	v_cndmask_b32_e64 v88, v23, v44, s[0:1]
	v_cndmask_b32_e64 v89, v90, v123, s[0:1]
	v_pk_add_f32 v[60:61], v[94:95], v[60:61]
	s_waitcnt lgkmcnt(4)
	v_pk_add_f32 v[76:77], v[76:77], v[82:83]
	ds_bpermute_b32 v80, v187, v39
	v_cndmask_b32_e32 v39, v42, v66, vcc
	s_waitcnt lgkmcnt(3)
; __device__ __forceinline__ float wave_reduce32(const float (&v)[32], int lane) {
;     ...
;     { const bool h = lane & 16;
; #pragma unroll
;       for (int t = 0; t < 8; ++t) { const float keep = h ? a[t + 8] : a[t], send = h ? a[t] : a[t + 8]; b[t] = keep + __shfl_xor(send, 16); } }
;     { const bool h = lane & 8;
; #pragma unroll
;       for (int t = 0; t < 4; ++t) { const float keep = h ? b[t + 4] : b[t], send = h ? b[t] : b[t + 4]; c[t] = keep + __shfl_xor(send, 8); } }
;     { const bool h = lane & 4;
; #pragma unroll
;       for (int t = 0; t < 2; ++t) { const float keep = h ? c[t + 2] : c[t], send = h ? c[t] : c[t + 2]; d[t] = keep + __shfl_xor(send, 4); } }
;     { const bool h = lane & 2; const float keep = h ? d[1] : d[0], send = h ? d[0] : d[1]; e = keep + __shfl_xor(send, 2); }
;     e += __shfl_xor(e, 1);
;     return e;
; }
; __device__ __forceinline__ void conv_tile(const Params& p, int l, int item, const bf16* PROJ, bf16* CV, LAS float* sl) {
;     ...
;     const float r1 = wave_reduce32(y, lane), r2 = wave_reduce32(y2, lane);
;     const int tl = 16 * ((lane >> 5) & 1) + 8 * ((lane >> 4) & 1) + 4 * ((lane >> 3) & 1) + 2 * ((lane >> 2) & 1) + ((lane >> 1) & 1);
;     __syncthreads();
;     if ((lane & 1) == 0) { part[(tl * 8 + wave) * 2] = r1; part[(tl * 8 + wave) * 2 + 1] = r2; }
	v_pk_add_f32 v[68:69], v[86:87], v[68:69]
	v_pk_add_f32 v[50:51], v[88:89], v[50:51]
	v_cndmask_b32_e64 v88, v15, v31, s[0:1]
	v_cndmask_b32_e64 v89, v138, v131, s[0:1]
	v_cndmask_b32_e32 v35, v60, v76, vcc
	v_mul_f32_e32 v124, v47, v47
	v_mul_f32_e32 v81, v26, v26
	ds_bpermute_b32 v84, v187, v39
	v_cndmask_b32_e32 v39, v48, v68, vcc
	s_waitcnt lgkmcnt(3)
	v_pk_add_f32 v[70:71], v[88:89], v[70:71]
	ds_bpermute_b32 v82, v187, v35
	v_cndmask_b32_e32 v35, v7, v63, vcc
	v_cndmask_b32_e64 v57, v124, v81, s[0:1]
	ds_bpermute_b32 v86, v187, v39
	v_cndmask_b32_e32 v39, v50, v70, vcc
	ds_bpermute_b32 v75, v187, v35
	v_cndmask_b32_e32 v35, v51, v71, vcc
	v_mul_f32_e32 v132, v33, v33
	v_mul_f32_e32 v139, v18, v18
	ds_bpermute_b32 v57, v186, v57
	ds_bpermute_b32 v59, v186, v59
	ds_bpermute_b32 v88, v187, v39
	ds_bpermute_b32 v89, v187, v35
	v_cndmask_b32_e64 v73, v132, v139, s[0:1]
	ds_bpermute_b32 v73, v186, v73
	v_and_b32_e32 v40, 8, v2
	v_cndmask_b32_e64 v90, v26, v47, s[0:1]
	v_cndmask_b32_e64 v91, v81, v124, s[0:1]
	v_cndmask_b32_e64 v92, v21, v36, s[0:1]
	v_cndmask_b32_e32 v7, v63, v7, vcc
	v_cndmask_b32_e32 v6, v62, v6, vcc
	v_cndmask_b32_e32 v51, v71, v51, vcc
	v_cndmask_b32_e32 v50, v70, v50, vcc
	s_waitcnt lgkmcnt(4)
	v_pk_add_f32 v[56:57], v[90:91], v[56:57]
	v_cndmask_b32_e64 v90, v18, v33, s[0:1]
	v_cndmask_b32_e64 v91, v139, v132, s[0:1]
	s_waitcnt lgkmcnt(3)
	v_pk_add_f32 v[58:59], v[92:93], v[58:59]
	v_cndmask_b32_e64 v92, v14, v29, s[0:1]
	v_cndmask_b32_e64 v93, v140, v133, s[0:1]
	v_pk_add_f32 v[6:7], v[6:7], v[74:75]
	s_waitcnt lgkmcnt(1)
	v_pk_add_f32 v[50:51], v[50:51], v[88:89]
	v_cmp_eq_u32_e64 s[0:1], 0, v40
	s_waitcnt lgkmcnt(0)
	v_pk_add_f32 v[72:73], v[90:91], v[72:73]
	v_cndmask_b32_e32 v8, v64, v8, vcc
	v_cndmask_b32_e64 v35, v6, v50, s[0:1]
	ds_bpermute_b32 v62, v180, v35
	v_cndmask_b32_e32 v35, v9, v65, vcc
	v_cndmask_b32_e32 v39, v56, v72, vcc
	ds_bpermute_b32 v81, v187, v35
	v_cndmask_b32_e32 v35, v57, v73, vcc
	ds_bpermute_b32 v90, v187, v39
	ds_bpermute_b32 v91, v187, v35
	v_cndmask_b32_e32 v9, v65, v9, vcc
	v_cndmask_b32_e32 v57, v73, v57, vcc
	v_cndmask_b32_e32 v56, v72, v56, vcc
	s_waitcnt lgkmcnt(2)
	v_pk_add_f32 v[8:9], v[8:9], v[80:81]
	s_waitcnt lgkmcnt(0)
	v_pk_add_f32 v[56:57], v[56:57], v[90:91]
	v_pk_add_f32 v[78:79], v[92:93], v[78:79]
	v_cndmask_b32_e64 v35, v8, v56, s[0:1]
	ds_bpermute_b32 v64, v180, v35
	v_cndmask_b32_e32 v35, v43, v67, vcc
	v_cndmask_b32_e32 v39, v58, v78, vcc
	ds_bpermute_b32 v85, v187, v35
	v_cndmask_b32_e32 v35, v59, v79, vcc
	ds_bpermute_b32 v92, v187, v39
	ds_bpermute_b32 v93, v187, v35
	v_cndmask_b32_e32 v43, v67, v43, vcc
	v_cndmask_b32_e32 v42, v66, v42, vcc
	v_cndmask_b32_e32 v59, v79, v59, vcc
	v_cndmask_b32_e32 v58, v78, v58, vcc
	s_waitcnt lgkmcnt(2)
	v_pk_add_f32 v[42:43], v[42:43], v[84:85]
	s_waitcnt lgkmcnt(0)
	v_pk_add_f32 v[58:59], v[58:59], v[92:93]
	v_cndmask_b32_e32 v48, v68, v48, vcc
	v_cndmask_b32_e64 v35, v42, v58, s[0:1]
	ds_bpermute_b32 v66, v180, v35
	v_cndmask_b32_e32 v35, v49, v69, vcc
	ds_bpermute_b32 v87, v187, v35
	v_cndmask_b32_e32 v35, v61, v77, vcc
	ds_bpermute_b32 v83, v187, v35
	v_cndmask_b32_e32 v49, v69, v49, vcc
	v_cndmask_b32_e32 v61, v77, v61, vcc
	v_cndmask_b32_e32 v60, v76, v60, vcc
	s_waitcnt lgkmcnt(1)
	v_pk_add_f32 v[48:49], v[48:49], v[86:87]
	s_waitcnt lgkmcnt(0)
	v_pk_add_f32 v[60:61], v[60:61], v[82:83]
	v_and_b32_e32 v45, 4, v2
	v_cndmask_b32_e64 v35, v48, v60, s[0:1]
	ds_bpermute_b32 v68, v180, v35
	v_cndmask_b32_e64 v35, v7, v51, s[0:1]
	ds_bpermute_b32 v63, v180, v35
	v_cndmask_b32_e64 v35, v43, v59, s[0:1]
	ds_bpermute_b32 v67, v180, v35
	v_cndmask_b32_e64 v7, v51, v7, s[0:1]
	v_cndmask_b32_e64 v6, v50, v6, s[0:1]
	v_cndmask_b32_e64 v43, v59, v43, s[0:1]
	v_cndmask_b32_e64 v42, v58, v42, s[0:1]
	s_waitcnt lgkmcnt(1)
	v_pk_add_f32 v[6:7], v[6:7], v[62:63]
	s_waitcnt lgkmcnt(0)
	v_pk_add_f32 v[42:43], v[42:43], v[66:67]
	v_cmp_eq_u32_e32 vcc, 0, v45
	v_cndmask_b32_e64 v8, v56, v8, s[0:1]
	v_cndmask_b32_e64 v48, v60, v48, s[0:1]
	v_cndmask_b32_e32 v35, v6, v42, vcc
	ds_bpermute_b32 v50, v179, v35
	v_cndmask_b32_e64 v35, v9, v57, s[0:1]
	ds_bpermute_b32 v65, v180, v35
	v_cndmask_b32_e64 v35, v49, v61, s[0:1]
	ds_bpermute_b32 v69, v180, v35
	v_cndmask_b32_e64 v9, v57, v9, s[0:1]
	v_cndmask_b32_e64 v49, v61, v49, s[0:1]
	s_waitcnt lgkmcnt(1)
	v_pk_add_f32 v[8:9], v[8:9], v[64:65]
	v_and_b32_e32 v46, 2, v2
	s_waitcnt lgkmcnt(0)
	v_pk_add_f32 v[48:49], v[48:49], v[68:69]
	v_cndmask_b32_e32 v6, v42, v6, vcc
	v_cndmask_b32_e32 v35, v8, v48, vcc
	ds_bpermute_b32 v56, v179, v35
	v_cndmask_b32_e32 v35, v7, v43, vcc
	ds_bpermute_b32 v51, v179, v35
	v_cndmask_b32_e32 v35, v9, v49, vcc
	ds_bpermute_b32 v57, v179, v35
	v_cndmask_b32_e32 v7, v43, v7, vcc
	v_cndmask_b32_e32 v9, v49, v9, vcc
	v_cndmask_b32_e32 v8, v48, v8, vcc
	s_waitcnt lgkmcnt(1)
	v_pk_add_f32 v[6:7], v[6:7], v[50:51]
	s_waitcnt lgkmcnt(0)
	v_pk_add_f32 v[8:9], v[8:9], v[56:57]
	v_cmp_eq_u32_e32 vcc, 0, v46
	v_readfirstlane_b32 s9, v2
	v_readlane_b32 s81, v251, 34
	v_cndmask_b32_e32 v35, v6, v8, vcc
	ds_bpermute_b32 v42, v178, v35
	v_cndmask_b32_e32 v35, v7, v9, vcc
	ds_bpermute_b32 v43, v178, v35
	v_cndmask_b32_e32 v7, v9, v7, vcc
	v_cndmask_b32_e32 v6, v8, v6, vcc
	v_and_b32_e32 v35, 1, v2
	v_cmp_eq_u32_e32 vcc, 0, v35
	s_waitcnt lgkmcnt(0)
	v_pk_add_f32 v[6:7], v[6:7], v[42:43]
	ds_bpermute_b32 v8, v162, v6
	ds_bpermute_b32 v9, v162, v7
	v_readlane_b32 s82, v251, 35
	v_readlane_b32 s83, v251, 36
	v_readlane_b32 s86, v251, 39
	v_readlane_b32 s87, v251, 40
	v_readlane_b32 s88, v251, 41
	v_readlane_b32 s89, v251, 42
	v_readlane_b32 s90, v251, 43
	v_readlane_b32 s91, v251, 44
	v_readlane_b32 s92, v251, 45
	v_readlane_b32 s93, v251, 46
	v_readlane_b32 s94, v251, 47
	v_readlane_b32 s95, v251, 48
	s_waitcnt lgkmcnt(0)
	s_barrier
	s_and_saveexec_b64 s[0:1], vcc
	s_cbranch_execz .LBB0_347
	s_ashr_i32 s9, s9, 5
	s_lshl_b32 s9, s9, 2
	v_lshlrev_b32_e32 v35, 5, v2
	s_and_b32 s9, s9, -8
	v_and_b32_e32 v35, 0x7c0, v35
	s_add_i32 s9, s9, 0
	v_add_u32_e32 v35, s9, v35
	v_add_u32_e32 v35, 0x20000, v35
	v_pk_add_f32 v[6:7], v[6:7], v[8:9]
	ds_write_b64 v35, v[6:7]
